# page loop: last iteration peeled so no loads are issued before the page's first row
# speedup vs baseline: 1.0014x; 1.0014x over previous
.Lpg_loop:
	s_waitcnt vmcnt(24)
	v_pk_mul_f32 v[98:99], v[116:117], v[52:53]
	v_pk_mul_f32 v[100:101], v[116:117], v[60:61]
	v_pk_mul_f32 v[174:175], v[116:117], v[56:57]
	v_pk_mul_f32 v[176:177], v[116:117], v[64:65]
	v_pk_fma_f32 v[98:99], v[114:115], v[50:51], v[98:99]
	v_pk_fma_f32 v[100:101], v[114:115], v[58:59], v[100:101]
	v_pk_fma_f32 v[174:175], v[114:115], v[54:55], v[174:175]
	v_pk_fma_f32 v[176:177], v[114:115], v[62:63], v[176:177]
	v_add_f32_e32 v136, v98, v99
	v_add_f32_e32 v137, v100, v101
	v_add_f32_e32 v138, v174, v175
	v_add_f32_e32 v139, v176, v177
	v_pk_mul_f32 v[98:99], v[112:113], v[52:53]
	v_pk_mul_f32 v[100:101], v[112:113], v[60:61]
	v_pk_mul_f32 v[174:175], v[112:113], v[56:57]
	v_pk_mul_f32 v[176:177], v[112:113], v[64:65]
	v_pk_fma_f32 v[98:99], v[110:111], v[50:51], v[98:99]
	v_pk_fma_f32 v[100:101], v[110:111], v[58:59], v[100:101]
	v_pk_fma_f32 v[174:175], v[110:111], v[54:55], v[174:175]
	v_pk_fma_f32 v[176:177], v[110:111], v[62:63], v[176:177]
	v_add_f32_e32 v140, v98, v99
	v_add_f32_e32 v141, v100, v101
	v_add_f32_e32 v142, v174, v175
	v_add_f32_e32 v144, v176, v177
	v_pk_mul_f32 v[98:99], v[108:109], v[52:53]
	v_pk_mul_f32 v[100:101], v[108:109], v[60:61]
	v_pk_mul_f32 v[174:175], v[108:109], v[56:57]
	v_pk_mul_f32 v[176:177], v[108:109], v[64:65]
	v_pk_fma_f32 v[98:99], v[106:107], v[50:51], v[98:99]
	v_pk_fma_f32 v[100:101], v[106:107], v[58:59], v[100:101]
	v_pk_fma_f32 v[174:175], v[106:107], v[54:55], v[174:175]
	v_pk_fma_f32 v[176:177], v[106:107], v[62:63], v[176:177]
	v_add_f32_e32 v147, v98, v99
	v_add_f32_e32 v148, v100, v101
	v_add_f32_e32 v149, v174, v175
	v_add_f32_e32 v150, v176, v177
	v_pk_mul_f32 v[98:99], v[104:105], v[52:53]
	v_pk_mul_f32 v[100:101], v[104:105], v[60:61]
	v_pk_mul_f32 v[174:175], v[104:105], v[56:57]
	v_pk_mul_f32 v[176:177], v[104:105], v[64:65]
	v_pk_fma_f32 v[98:99], v[102:103], v[50:51], v[98:99]
	v_pk_fma_f32 v[100:101], v[102:103], v[58:59], v[100:101]
	v_pk_fma_f32 v[174:175], v[102:103], v[54:55], v[174:175]
	v_pk_fma_f32 v[176:177], v[102:103], v[62:63], v[176:177]
	v_add_f32_e32 v151, v98, v99
	v_add_f32_e32 v152, v100, v101
	v_add_f32_e32 v153, v174, v175
	v_add_f32_e32 v154, v176, v177
	v_add_f32_e32 v155, v146, v171
	v_add_f32_e32 v156, v155, v170
	v_add_f32_e32 v157, v156, v169
	v_add_f32_dpp v136, v136, v136 row_mirror row_mask:0xf bank_mask:0x3 bound_ctrl:1
	v_add_f32_dpp v137, v137, v137 row_mirror row_mask:0xf bank_mask:0x3 bound_ctrl:1
	v_add_f32_dpp v138, v138, v138 row_mirror row_mask:0xf bank_mask:0x3 bound_ctrl:1
	v_add_f32_dpp v139, v139, v139 row_mirror row_mask:0xf bank_mask:0x3 bound_ctrl:1
	v_add_f32_dpp v140, v140, v140 row_mirror row_mask:0xf bank_mask:0x3 bound_ctrl:1
	v_add_f32_dpp v141, v141, v141 row_mirror row_mask:0xf bank_mask:0x3 bound_ctrl:1
	v_add_f32_dpp v142, v142, v142 row_mirror row_mask:0xf bank_mask:0x3 bound_ctrl:1
	v_add_f32_dpp v144, v144, v144 row_mirror row_mask:0xf bank_mask:0x3 bound_ctrl:1
	v_add_f32_dpp v136, v147, v147 row_mirror row_mask:0xf bank_mask:0xc bound_ctrl:1
	v_add_f32_dpp v137, v148, v148 row_mirror row_mask:0xf bank_mask:0xc bound_ctrl:1
	v_add_f32_dpp v138, v149, v149 row_mirror row_mask:0xf bank_mask:0xc bound_ctrl:1
	v_add_f32_dpp v139, v150, v150 row_mirror row_mask:0xf bank_mask:0xc bound_ctrl:1
	v_add_f32_dpp v140, v151, v151 row_mirror row_mask:0xf bank_mask:0xc bound_ctrl:1
	v_add_f32_dpp v141, v152, v152 row_mirror row_mask:0xf bank_mask:0xc bound_ctrl:1
	v_add_f32_dpp v142, v153, v153 row_mirror row_mask:0xf bank_mask:0xc bound_ctrl:1
	v_add_f32_dpp v144, v154, v154 row_mirror row_mask:0xf bank_mask:0xc bound_ctrl:1
	v_add_f32_dpp v136, v136, v136 row_half_mirror row_mask:0xf bank_mask:0x5 bound_ctrl:1
	v_add_f32_dpp v137, v137, v137 row_half_mirror row_mask:0xf bank_mask:0x5 bound_ctrl:1
	v_add_f32_dpp v138, v138, v138 row_half_mirror row_mask:0xf bank_mask:0x5 bound_ctrl:1
	v_add_f32_dpp v139, v139, v139 row_half_mirror row_mask:0xf bank_mask:0x5 bound_ctrl:1
	v_add_f32_dpp v136, v140, v140 row_half_mirror row_mask:0xf bank_mask:0xa bound_ctrl:1
	v_add_f32_dpp v137, v141, v141 row_half_mirror row_mask:0xf bank_mask:0xa bound_ctrl:1
	v_add_f32_dpp v138, v142, v142 row_half_mirror row_mask:0xf bank_mask:0xa bound_ctrl:1
	v_add_f32_dpp v139, v144, v144 row_half_mirror row_mask:0xf bank_mask:0xa bound_ctrl:1
	v_add_f32_dpp v136, v136, v136 quad_perm:[2,3,0,1] row_mask:0xf bank_mask:0xf bound_ctrl:1
	v_add_f32_dpp v138, v138, v138 quad_perm:[2,3,0,1] row_mask:0xf bank_mask:0xf bound_ctrl:1
	v_add_f32_dpp v137, v137, v137 quad_perm:[2,3,0,1] row_mask:0xf bank_mask:0xf bound_ctrl:1
	v_add_f32_dpp v139, v139, v139 quad_perm:[2,3,0,1] row_mask:0xf bank_mask:0xf bound_ctrl:1
	v_cndmask_b32_e64 v173, v155, v146, s[28:29]
	v_cndmask_b32_e64 v178, v157, v156, s[28:29]
	v_cndmask_b32_e64 v136, v136, v138, s[24:25]
	v_cndmask_b32_e64 v137, v137, v139, s[24:25]
	v_cndmask_b32_e64 v173, v178, v173, s[24:25]
	v_add_f32_e32 v146, v157, v167
	v_add_f32_dpp v136, v136, v136 quad_perm:[1,0,3,2] row_mask:0xf bank_mask:0xf bound_ctrl:1
	v_add_f32_dpp v137, v137, v137 quad_perm:[1,0,3,2] row_mask:0xf bank_mask:0xf bound_ctrl:1
	v_cndmask_b32_e64 v136, v136, v137, s[28:29]
	v_fmac_f32_e32 v136, 0x3fb8aa3b, v173
	s_nop 1
	v_max_f32_dpp v179, v136, v136 quad_perm:[1,0,3,2] row_mask:0xf bank_mask:0xf bound_ctrl:1
	s_nop 1
	v_max_f32_dpp v180, v179, v179 quad_perm:[2,3,0,1] row_mask:0xf bank_mask:0xf bound_ctrl:1
	v_max_f32_e32 v180, v134, v180
	v_sub_f32_e32 v155, v134, v180
	v_sub_f32_e32 v156, v136, v180
	v_mov_b32_e32 v134, v180
	v_exp_f32_e32 v155, v155
	v_exp_f32_e32 v156, v156
	s_nop 0
	v_mov_b32_dpp v137, v155 row_newbcast:0 row_mask:0xf bank_mask:0xf
	v_mov_b32_dpp v142, v155 row_newbcast:4 row_mask:0xf bank_mask:0xf
	v_mov_b32_dpp v150, v155 row_newbcast:8 row_mask:0xf bank_mask:0xf
	v_mov_b32_dpp v178, v155 row_newbcast:12 row_mask:0xf bank_mask:0xf
	v_add_f32_dpp v157, v156, v156 quad_perm:[1,0,3,2] row_mask:0xf bank_mask:0xf bound_ctrl:1
	v_mov_b32_dpp v138, v156 row_newbcast:0 row_mask:0xf bank_mask:0xf
	v_mov_b32_dpp v139, v156 row_newbcast:1 row_mask:0xf bank_mask:0xf
	v_mov_b32_dpp v140, v156 row_newbcast:2 row_mask:0xf bank_mask:0xf
	v_mov_b32_dpp v141, v156 row_newbcast:3 row_mask:0xf bank_mask:0xf
	v_add_f32_dpp v173, v157, v157 quad_perm:[2,3,0,1] row_mask:0xf bank_mask:0xf bound_ctrl:1
	v_mov_b32_dpp v144, v156 row_newbcast:4 row_mask:0xf bank_mask:0xf
	v_mov_b32_dpp v147, v156 row_newbcast:5 row_mask:0xf bank_mask:0xf
	v_mov_b32_dpp v148, v156 row_newbcast:6 row_mask:0xf bank_mask:0xf
	v_mov_b32_dpp v149, v156 row_newbcast:7 row_mask:0xf bank_mask:0xf
	v_fma_f32 v135, v135, v155, v173
	v_mov_b32_dpp v151, v156 row_newbcast:8 row_mask:0xf bank_mask:0xf
	v_mov_b32_dpp v152, v156 row_newbcast:9 row_mask:0xf bank_mask:0xf
	v_mov_b32_dpp v153, v156 row_newbcast:10 row_mask:0xf bank_mask:0xf
	v_mov_b32_dpp v154, v156 row_newbcast:11 row_mask:0xf bank_mask:0xf
	v_mov_b32_dpp v179, v156 row_newbcast:12 row_mask:0xf bank_mask:0xf
	v_mov_b32_dpp v180, v156 row_newbcast:13 row_mask:0xf bank_mask:0xf
	v_mov_b32_dpp v181, v156 row_newbcast:14 row_mask:0xf bank_mask:0xf
	v_mov_b32_dpp v0, v156 row_newbcast:15 row_mask:0xf bank_mask:0xf
	v_pk_mul_f32 v[118:119], v[118:119], v[136:137] op_sel:[0,1] op_sel_hi:[1,1]
	v_pk_mul_f32 v[120:121], v[120:121], v[136:137] op_sel:[0,1] op_sel_hi:[1,1]
	v_pk_mul_f32 v[122:123], v[122:123], v[142:143] op_sel:[0,0] op_sel_hi:[1,0]
	v_pk_mul_f32 v[124:125], v[124:125], v[142:143] op_sel:[0,0] op_sel_hi:[1,0]
	v_pk_mul_f32 v[126:127], v[126:127], v[150:151] op_sel:[0,0] op_sel_hi:[1,0]
	v_pk_mul_f32 v[128:129], v[128:129], v[150:151] op_sel:[0,0] op_sel_hi:[1,0]
	v_pk_mul_f32 v[130:131], v[130:131], v[178:179] op_sel:[0,0] op_sel_hi:[1,0]
	v_pk_mul_f32 v[132:133], v[132:133], v[178:179] op_sel:[0,0] op_sel_hi:[1,0]
	v_pk_fma_f32 v[118:119], v[138:139], v[22:23], v[118:119] op_sel:[0,0,0] op_sel_hi:[0,1,1]
	v_pk_fma_f32 v[120:121], v[138:139], v[24:25], v[120:121] op_sel:[0,0,0] op_sel_hi:[0,1,1]
	v_pk_fma_f32 v[122:123], v[144:145], v[22:23], v[122:123] op_sel:[0,0,0] op_sel_hi:[0,1,1]
	v_pk_fma_f32 v[124:125], v[144:145], v[24:25], v[124:125] op_sel:[0,0,0] op_sel_hi:[0,1,1]
	v_pk_fma_f32 v[126:127], v[150:151], v[22:23], v[126:127] op_sel:[1,0,0] op_sel_hi:[1,1,1]
	v_pk_fma_f32 v[128:129], v[150:151], v[24:25], v[128:129] op_sel:[1,0,0] op_sel_hi:[1,1,1]
	v_pk_fma_f32 v[130:131], v[178:179], v[22:23], v[130:131] op_sel:[1,0,0] op_sel_hi:[1,1,1]
	v_pk_fma_f32 v[132:133], v[178:179], v[24:25], v[132:133] op_sel:[1,0,0] op_sel_hi:[1,1,1]
	v_pk_fma_f32 v[118:119], v[138:139], v[18:19], v[118:119] op_sel:[1,0,0] op_sel_hi:[1,1,1]
	v_pk_fma_f32 v[120:121], v[138:139], v[20:21], v[120:121] op_sel:[1,0,0] op_sel_hi:[1,1,1]
	v_pk_fma_f32 v[122:123], v[146:147], v[18:19], v[122:123] op_sel:[1,0,0] op_sel_hi:[1,1,1]
	v_pk_fma_f32 v[124:125], v[146:147], v[20:21], v[124:125] op_sel:[1,0,0] op_sel_hi:[1,1,1]
	v_pk_fma_f32 v[126:127], v[152:153], v[18:19], v[126:127] op_sel:[0,0,0] op_sel_hi:[0,1,1]
	v_pk_fma_f32 v[128:129], v[152:153], v[20:21], v[128:129] op_sel:[0,0,0] op_sel_hi:[0,1,1]
	v_pk_fma_f32 v[130:131], v[180:181], v[18:19], v[130:131] op_sel:[0,0,0] op_sel_hi:[0,1,1]
	v_pk_fma_f32 v[132:133], v[180:181], v[20:21], v[132:133] op_sel:[0,0,0] op_sel_hi:[0,1,1]
	v_pk_fma_f32 v[118:119], v[140:141], v[26:27], v[118:119] op_sel:[0,0,0] op_sel_hi:[0,1,1]
	v_pk_fma_f32 v[120:121], v[140:141], v[28:29], v[120:121] op_sel:[0,0,0] op_sel_hi:[0,1,1]
	v_pk_fma_f32 v[122:123], v[148:149], v[26:27], v[122:123] op_sel:[0,0,0] op_sel_hi:[0,1,1]
	v_pk_fma_f32 v[124:125], v[148:149], v[28:29], v[124:125] op_sel:[0,0,0] op_sel_hi:[0,1,1]
	v_pk_fma_f32 v[126:127], v[152:153], v[26:27], v[126:127] op_sel:[1,0,0] op_sel_hi:[1,1,1]
	v_pk_fma_f32 v[128:129], v[152:153], v[28:29], v[128:129] op_sel:[1,0,0] op_sel_hi:[1,1,1]
	v_pk_fma_f32 v[130:131], v[180:181], v[26:27], v[130:131] op_sel:[1,0,0] op_sel_hi:[1,1,1]
	v_pk_fma_f32 v[132:133], v[180:181], v[28:29], v[132:133] op_sel:[1,0,0] op_sel_hi:[1,1,1]
	v_pk_fma_f32 v[118:119], v[140:141], v[30:31], v[118:119] op_sel:[1,0,0] op_sel_hi:[1,1,1]
	v_pk_fma_f32 v[120:121], v[140:141], v[32:33], v[120:121] op_sel:[1,0,0] op_sel_hi:[1,1,1]
	v_pk_fma_f32 v[122:123], v[148:149], v[30:31], v[122:123] op_sel:[1,0,0] op_sel_hi:[1,1,1]
	v_pk_fma_f32 v[124:125], v[148:149], v[32:33], v[124:125] op_sel:[1,0,0] op_sel_hi:[1,1,1]
	v_pk_fma_f32 v[126:127], v[154:155], v[30:31], v[126:127] op_sel:[0,0,0] op_sel_hi:[0,1,1]
	v_pk_fma_f32 v[128:129], v[154:155], v[32:33], v[128:129] op_sel:[0,0,0] op_sel_hi:[0,1,1]
	v_pk_fma_f32 v[130:131], v[0:1], v[30:31], v[130:131] op_sel:[0,0,0] op_sel_hi:[0,1,1]
	v_pk_fma_f32 v[132:133], v[0:1], v[32:33], v[132:133] op_sel:[0,0,0] op_sel_hi:[0,1,1]
	s_add_i32 s0, s8, 0x2000
	s_mov_b32 s6, s14
	s_mov_b32 s7, s15
	buffer_load_dwordx4 v[50:53], v161, s[12:15], s0 offen nt
	buffer_load_dwordx4 v[22:25], v161, s[4:7], s0 offen nt
	s_add_i32 s0, s3, 0x80
	buffer_load_dword v167, v162, s[16:19], s0 offen
	s_add_i32 s0, s8, 0x2400
	buffer_load_dwordx4 v[58:61], v161, s[12:15], s0 offen nt
	buffer_load_dwordx4 v[18:21], v161, s[4:7], s0 offen nt
	s_add_i32 s0, s3, 0x90
	buffer_load_dword v169, v162, s[16:19], s0 offen
	s_add_i32 s0, s8, 0x2800
	buffer_load_dwordx4 v[54:57], v161, s[12:15], s0 offen nt
	buffer_load_dwordx4 v[26:29], v161, s[4:7], s0 offen nt
	s_add_i32 s0, s3, 0xa0
	buffer_load_dword v170, v162, s[16:19], s0 offen
	s_add_i32 s0, s8, 0x2c00
	buffer_load_dwordx4 v[62:65], v161, s[12:15], s0 offen nt
	buffer_load_dwordx4 v[30:33], v161, s[4:7], s0 offen nt
	s_add_i32 s0, s3, 0xb0
	buffer_load_dword v171, v162, s[16:19], s0 offen
	s_waitcnt vmcnt(24)
	v_pk_mul_f32 v[98:99], v[116:117], v[36:37]
	v_pk_mul_f32 v[100:101], v[116:117], v[44:45]
	v_pk_mul_f32 v[174:175], v[116:117], v[40:41]
	v_pk_mul_f32 v[176:177], v[116:117], v[48:49]
	v_pk_fma_f32 v[98:99], v[114:115], v[34:35], v[98:99]
	v_pk_fma_f32 v[100:101], v[114:115], v[42:43], v[100:101]
	v_pk_fma_f32 v[174:175], v[114:115], v[38:39], v[174:175]
	v_pk_fma_f32 v[176:177], v[114:115], v[46:47], v[176:177]
	v_add_f32_e32 v136, v98, v99
	v_add_f32_e32 v137, v100, v101
	v_add_f32_e32 v138, v174, v175
	v_add_f32_e32 v139, v176, v177
	v_pk_mul_f32 v[98:99], v[112:113], v[36:37]
	v_pk_mul_f32 v[100:101], v[112:113], v[44:45]
	v_pk_mul_f32 v[174:175], v[112:113], v[40:41]
	v_pk_mul_f32 v[176:177], v[112:113], v[48:49]
	v_pk_fma_f32 v[98:99], v[110:111], v[34:35], v[98:99]
	v_pk_fma_f32 v[100:101], v[110:111], v[42:43], v[100:101]
	v_pk_fma_f32 v[174:175], v[110:111], v[38:39], v[174:175]
	v_pk_fma_f32 v[176:177], v[110:111], v[46:47], v[176:177]
	v_add_f32_e32 v140, v98, v99
	v_add_f32_e32 v141, v100, v101
	v_add_f32_e32 v142, v174, v175
	v_add_f32_e32 v144, v176, v177
	v_pk_mul_f32 v[98:99], v[108:109], v[36:37]
	v_pk_mul_f32 v[100:101], v[108:109], v[44:45]
	v_pk_mul_f32 v[174:175], v[108:109], v[40:41]
	v_pk_mul_f32 v[176:177], v[108:109], v[48:49]
	v_pk_fma_f32 v[98:99], v[106:107], v[34:35], v[98:99]
	v_pk_fma_f32 v[100:101], v[106:107], v[42:43], v[100:101]
	v_pk_fma_f32 v[174:175], v[106:107], v[38:39], v[174:175]
	v_pk_fma_f32 v[176:177], v[106:107], v[46:47], v[176:177]
	v_add_f32_e32 v147, v98, v99
	v_add_f32_e32 v148, v100, v101
	v_add_f32_e32 v149, v174, v175
	v_add_f32_e32 v150, v176, v177
	v_pk_mul_f32 v[98:99], v[104:105], v[36:37]
	v_pk_mul_f32 v[100:101], v[104:105], v[44:45]
	v_pk_mul_f32 v[174:175], v[104:105], v[40:41]
	v_pk_mul_f32 v[176:177], v[104:105], v[48:49]
	v_pk_fma_f32 v[98:99], v[102:103], v[34:35], v[98:99]
	v_pk_fma_f32 v[100:101], v[102:103], v[42:43], v[100:101]
	v_pk_fma_f32 v[174:175], v[102:103], v[38:39], v[174:175]
	v_pk_fma_f32 v[176:177], v[102:103], v[46:47], v[176:177]
	v_add_f32_e32 v151, v98, v99
	v_add_f32_e32 v152, v100, v101
	v_add_f32_e32 v153, v174, v175
	v_add_f32_e32 v154, v176, v177
	v_add_f32_e32 v155, v146, v166
	v_add_f32_e32 v156, v155, v165
	v_add_f32_e32 v157, v156, v164
	v_add_f32_dpp v136, v136, v136 row_mirror row_mask:0xf bank_mask:0x3 bound_ctrl:1
	v_add_f32_dpp v137, v137, v137 row_mirror row_mask:0xf bank_mask:0x3 bound_ctrl:1
	v_add_f32_dpp v138, v138, v138 row_mirror row_mask:0xf bank_mask:0x3 bound_ctrl:1
	v_add_f32_dpp v139, v139, v139 row_mirror row_mask:0xf bank_mask:0x3 bound_ctrl:1
	v_add_f32_dpp v140, v140, v140 row_mirror row_mask:0xf bank_mask:0x3 bound_ctrl:1
	v_add_f32_dpp v141, v141, v141 row_mirror row_mask:0xf bank_mask:0x3 bound_ctrl:1
	v_add_f32_dpp v142, v142, v142 row_mirror row_mask:0xf bank_mask:0x3 bound_ctrl:1
	v_add_f32_dpp v144, v144, v144 row_mirror row_mask:0xf bank_mask:0x3 bound_ctrl:1
	v_add_f32_dpp v136, v147, v147 row_mirror row_mask:0xf bank_mask:0xc bound_ctrl:1
	v_add_f32_dpp v137, v148, v148 row_mirror row_mask:0xf bank_mask:0xc bound_ctrl:1
	v_add_f32_dpp v138, v149, v149 row_mirror row_mask:0xf bank_mask:0xc bound_ctrl:1
	v_add_f32_dpp v139, v150, v150 row_mirror row_mask:0xf bank_mask:0xc bound_ctrl:1
	v_add_f32_dpp v140, v151, v151 row_mirror row_mask:0xf bank_mask:0xc bound_ctrl:1
	v_add_f32_dpp v141, v152, v152 row_mirror row_mask:0xf bank_mask:0xc bound_ctrl:1
	v_add_f32_dpp v142, v153, v153 row_mirror row_mask:0xf bank_mask:0xc bound_ctrl:1
	v_add_f32_dpp v144, v154, v154 row_mirror row_mask:0xf bank_mask:0xc bound_ctrl:1
	v_add_f32_dpp v136, v136, v136 row_half_mirror row_mask:0xf bank_mask:0x5 bound_ctrl:1
	v_add_f32_dpp v137, v137, v137 row_half_mirror row_mask:0xf bank_mask:0x5 bound_ctrl:1
	v_add_f32_dpp v138, v138, v138 row_half_mirror row_mask:0xf bank_mask:0x5 bound_ctrl:1
	v_add_f32_dpp v139, v139, v139 row_half_mirror row_mask:0xf bank_mask:0x5 bound_ctrl:1
	v_add_f32_dpp v136, v140, v140 row_half_mirror row_mask:0xf bank_mask:0xa bound_ctrl:1
	v_add_f32_dpp v137, v141, v141 row_half_mirror row_mask:0xf bank_mask:0xa bound_ctrl:1
	v_add_f32_dpp v138, v142, v142 row_half_mirror row_mask:0xf bank_mask:0xa bound_ctrl:1
	v_add_f32_dpp v139, v144, v144 row_half_mirror row_mask:0xf bank_mask:0xa bound_ctrl:1
	v_add_f32_dpp v136, v136, v136 quad_perm:[2,3,0,1] row_mask:0xf bank_mask:0xf bound_ctrl:1
	v_add_f32_dpp v138, v138, v138 quad_perm:[2,3,0,1] row_mask:0xf bank_mask:0xf bound_ctrl:1
	v_add_f32_dpp v137, v137, v137 quad_perm:[2,3,0,1] row_mask:0xf bank_mask:0xf bound_ctrl:1
	v_add_f32_dpp v139, v139, v139 quad_perm:[2,3,0,1] row_mask:0xf bank_mask:0xf bound_ctrl:1
	v_cndmask_b32_e64 v173, v155, v146, s[28:29]
	v_cndmask_b32_e64 v178, v157, v156, s[28:29]
	v_cndmask_b32_e64 v136, v136, v138, s[24:25]
	v_cndmask_b32_e64 v137, v137, v139, s[24:25]
	v_cndmask_b32_e64 v173, v178, v173, s[24:25]
	v_add_f32_e32 v146, v157, v168
	v_add_f32_dpp v136, v136, v136 quad_perm:[1,0,3,2] row_mask:0xf bank_mask:0xf bound_ctrl:1
	v_add_f32_dpp v137, v137, v137 quad_perm:[1,0,3,2] row_mask:0xf bank_mask:0xf bound_ctrl:1
	v_cndmask_b32_e64 v136, v136, v137, s[28:29]
	v_fmac_f32_e32 v136, 0x3fb8aa3b, v173
	s_nop 1
	v_max_f32_dpp v179, v136, v136 quad_perm:[1,0,3,2] row_mask:0xf bank_mask:0xf bound_ctrl:1
	s_nop 1
	v_max_f32_dpp v180, v179, v179 quad_perm:[2,3,0,1] row_mask:0xf bank_mask:0xf bound_ctrl:1
	v_max_f32_e32 v180, v134, v180
	v_sub_f32_e32 v155, v134, v180
	v_sub_f32_e32 v156, v136, v180
	v_mov_b32_e32 v134, v180
	v_exp_f32_e32 v155, v155
	v_exp_f32_e32 v156, v156
	s_nop 0
	v_mov_b32_dpp v137, v155 row_newbcast:0 row_mask:0xf bank_mask:0xf
	v_mov_b32_dpp v142, v155 row_newbcast:4 row_mask:0xf bank_mask:0xf
	v_mov_b32_dpp v150, v155 row_newbcast:8 row_mask:0xf bank_mask:0xf
	v_mov_b32_dpp v178, v155 row_newbcast:12 row_mask:0xf bank_mask:0xf
	v_add_f32_dpp v157, v156, v156 quad_perm:[1,0,3,2] row_mask:0xf bank_mask:0xf bound_ctrl:1
	v_mov_b32_dpp v138, v156 row_newbcast:0 row_mask:0xf bank_mask:0xf
	v_mov_b32_dpp v139, v156 row_newbcast:1 row_mask:0xf bank_mask:0xf
	v_mov_b32_dpp v140, v156 row_newbcast:2 row_mask:0xf bank_mask:0xf
	v_mov_b32_dpp v141, v156 row_newbcast:3 row_mask:0xf bank_mask:0xf
	v_add_f32_dpp v173, v157, v157 quad_perm:[2,3,0,1] row_mask:0xf bank_mask:0xf bound_ctrl:1
	v_mov_b32_dpp v144, v156 row_newbcast:4 row_mask:0xf bank_mask:0xf
	v_mov_b32_dpp v147, v156 row_newbcast:5 row_mask:0xf bank_mask:0xf
	v_mov_b32_dpp v148, v156 row_newbcast:6 row_mask:0xf bank_mask:0xf
	v_mov_b32_dpp v149, v156 row_newbcast:7 row_mask:0xf bank_mask:0xf
	v_fma_f32 v135, v135, v155, v173
	v_mov_b32_dpp v151, v156 row_newbcast:8 row_mask:0xf bank_mask:0xf
	v_mov_b32_dpp v152, v156 row_newbcast:9 row_mask:0xf bank_mask:0xf
	v_mov_b32_dpp v153, v156 row_newbcast:10 row_mask:0xf bank_mask:0xf
	v_mov_b32_dpp v154, v156 row_newbcast:11 row_mask:0xf bank_mask:0xf
	v_mov_b32_dpp v179, v156 row_newbcast:12 row_mask:0xf bank_mask:0xf
	v_mov_b32_dpp v180, v156 row_newbcast:13 row_mask:0xf bank_mask:0xf
	v_mov_b32_dpp v181, v156 row_newbcast:14 row_mask:0xf bank_mask:0xf
	v_mov_b32_dpp v0, v156 row_newbcast:15 row_mask:0xf bank_mask:0xf
	v_pk_mul_f32 v[118:119], v[118:119], v[136:137] op_sel:[0,1] op_sel_hi:[1,1]
	v_pk_mul_f32 v[120:121], v[120:121], v[136:137] op_sel:[0,1] op_sel_hi:[1,1]
	v_pk_mul_f32 v[122:123], v[122:123], v[142:143] op_sel:[0,0] op_sel_hi:[1,0]
	v_pk_mul_f32 v[124:125], v[124:125], v[142:143] op_sel:[0,0] op_sel_hi:[1,0]
	v_pk_mul_f32 v[126:127], v[126:127], v[150:151] op_sel:[0,0] op_sel_hi:[1,0]
	v_pk_mul_f32 v[128:129], v[128:129], v[150:151] op_sel:[0,0] op_sel_hi:[1,0]
	v_pk_mul_f32 v[130:131], v[130:131], v[178:179] op_sel:[0,0] op_sel_hi:[1,0]
	v_pk_mul_f32 v[132:133], v[132:133], v[178:179] op_sel:[0,0] op_sel_hi:[1,0]
	v_pk_fma_f32 v[118:119], v[138:139], v[2:3], v[118:119] op_sel:[0,0,0] op_sel_hi:[0,1,1]
	v_pk_fma_f32 v[120:121], v[138:139], v[4:5], v[120:121] op_sel:[0,0,0] op_sel_hi:[0,1,1]
	v_pk_fma_f32 v[122:123], v[144:145], v[2:3], v[122:123] op_sel:[0,0,0] op_sel_hi:[0,1,1]
	v_pk_fma_f32 v[124:125], v[144:145], v[4:5], v[124:125] op_sel:[0,0,0] op_sel_hi:[0,1,1]
	v_pk_fma_f32 v[126:127], v[150:151], v[2:3], v[126:127] op_sel:[1,0,0] op_sel_hi:[1,1,1]
	v_pk_fma_f32 v[128:129], v[150:151], v[4:5], v[128:129] op_sel:[1,0,0] op_sel_hi:[1,1,1]
	v_pk_fma_f32 v[130:131], v[178:179], v[2:3], v[130:131] op_sel:[1,0,0] op_sel_hi:[1,1,1]
	v_pk_fma_f32 v[132:133], v[178:179], v[4:5], v[132:133] op_sel:[1,0,0] op_sel_hi:[1,1,1]
	v_pk_fma_f32 v[118:119], v[138:139], v[6:7], v[118:119] op_sel:[1,0,0] op_sel_hi:[1,1,1]
	v_pk_fma_f32 v[120:121], v[138:139], v[8:9], v[120:121] op_sel:[1,0,0] op_sel_hi:[1,1,1]
	v_pk_fma_f32 v[122:123], v[146:147], v[6:7], v[122:123] op_sel:[1,0,0] op_sel_hi:[1,1,1]
	v_pk_fma_f32 v[124:125], v[146:147], v[8:9], v[124:125] op_sel:[1,0,0] op_sel_hi:[1,1,1]
	v_pk_fma_f32 v[126:127], v[152:153], v[6:7], v[126:127] op_sel:[0,0,0] op_sel_hi:[0,1,1]
	v_pk_fma_f32 v[128:129], v[152:153], v[8:9], v[128:129] op_sel:[0,0,0] op_sel_hi:[0,1,1]
	v_pk_fma_f32 v[130:131], v[180:181], v[6:7], v[130:131] op_sel:[0,0,0] op_sel_hi:[0,1,1]
	v_pk_fma_f32 v[132:133], v[180:181], v[8:9], v[132:133] op_sel:[0,0,0] op_sel_hi:[0,1,1]
	v_pk_fma_f32 v[118:119], v[140:141], v[10:11], v[118:119] op_sel:[0,0,0] op_sel_hi:[0,1,1]
	v_pk_fma_f32 v[120:121], v[140:141], v[12:13], v[120:121] op_sel:[0,0,0] op_sel_hi:[0,1,1]
	v_pk_fma_f32 v[122:123], v[148:149], v[10:11], v[122:123] op_sel:[0,0,0] op_sel_hi:[0,1,1]
	v_pk_fma_f32 v[124:125], v[148:149], v[12:13], v[124:125] op_sel:[0,0,0] op_sel_hi:[0,1,1]
	v_pk_fma_f32 v[126:127], v[152:153], v[10:11], v[126:127] op_sel:[1,0,0] op_sel_hi:[1,1,1]
	v_pk_fma_f32 v[128:129], v[152:153], v[12:13], v[128:129] op_sel:[1,0,0] op_sel_hi:[1,1,1]
	v_pk_fma_f32 v[130:131], v[180:181], v[10:11], v[130:131] op_sel:[1,0,0] op_sel_hi:[1,1,1]
	v_pk_fma_f32 v[132:133], v[180:181], v[12:13], v[132:133] op_sel:[1,0,0] op_sel_hi:[1,1,1]
	v_pk_fma_f32 v[118:119], v[140:141], v[14:15], v[118:119] op_sel:[1,0,0] op_sel_hi:[1,1,1]
	v_pk_fma_f32 v[120:121], v[140:141], v[16:17], v[120:121] op_sel:[1,0,0] op_sel_hi:[1,1,1]
	v_pk_fma_f32 v[122:123], v[148:149], v[14:15], v[122:123] op_sel:[1,0,0] op_sel_hi:[1,1,1]
	v_pk_fma_f32 v[124:125], v[148:149], v[16:17], v[124:125] op_sel:[1,0,0] op_sel_hi:[1,1,1]
	v_pk_fma_f32 v[126:127], v[154:155], v[14:15], v[126:127] op_sel:[0,0,0] op_sel_hi:[0,1,1]
	v_pk_fma_f32 v[128:129], v[154:155], v[16:17], v[128:129] op_sel:[0,0,0] op_sel_hi:[0,1,1]
	v_pk_fma_f32 v[130:131], v[0:1], v[14:15], v[130:131] op_sel:[0,0,0] op_sel_hi:[0,1,1]
	v_pk_fma_f32 v[132:133], v[0:1], v[16:17], v[132:133] op_sel:[0,0,0] op_sel_hi:[0,1,1]
	s_add_i32 s0, s8, 0x1000
	buffer_load_dwordx4 v[34:37], v161, s[12:15], s0 offen nt
	buffer_load_dwordx4 v[2:5], v161, s[4:7], s0 offen nt
	s_add_i32 s0, s3, 64
	buffer_load_dword v168, v162, s[16:19], s0 offen
	s_add_i32 s0, s8, 0x1400
	buffer_load_dwordx4 v[42:45], v161, s[12:15], s0 offen nt
	buffer_load_dwordx4 v[6:9], v161, s[4:7], s0 offen nt
	s_add_i32 s0, s3, 0x50
	buffer_load_dword v164, v162, s[16:19], s0 offen
	s_add_i32 s0, s8, 0x1800
	buffer_load_dwordx4 v[38:41], v161, s[12:15], s0 offen nt
	buffer_load_dwordx4 v[10:13], v161, s[4:7], s0 offen nt
	s_add_i32 s0, s3, 0x60
	buffer_load_dword v165, v162, s[16:19], s0 offen
	s_add_i32 s0, s8, 0x1c00
	buffer_load_dwordx4 v[46:49], v161, s[12:15], s0 offen nt
	buffer_load_dwordx4 v[14:17], v161, s[4:7], s0 offen nt
	s_add_i32 s0, s3, 0x70
	buffer_load_dword v166, v162, s[16:19], s0 offen
	s_waitcnt vmcnt(24)
	v_pk_mul_f32 v[98:99], v[116:117], v[84:85]
	v_pk_mul_f32 v[100:101], v[116:117], v[88:89]
	v_pk_mul_f32 v[174:175], v[116:117], v[92:93]
	v_pk_mul_f32 v[176:177], v[116:117], v[96:97]
	v_pk_fma_f32 v[98:99], v[114:115], v[82:83], v[98:99]
	v_pk_fma_f32 v[100:101], v[114:115], v[86:87], v[100:101]
	v_pk_fma_f32 v[174:175], v[114:115], v[90:91], v[174:175]
	v_pk_fma_f32 v[176:177], v[114:115], v[94:95], v[176:177]
	v_add_f32_e32 v136, v98, v99
	v_add_f32_e32 v137, v100, v101
	v_add_f32_e32 v138, v174, v175
	v_add_f32_e32 v139, v176, v177
	v_pk_mul_f32 v[98:99], v[112:113], v[84:85]
	v_pk_mul_f32 v[100:101], v[112:113], v[88:89]
	v_pk_mul_f32 v[174:175], v[112:113], v[92:93]
	v_pk_mul_f32 v[176:177], v[112:113], v[96:97]
	v_pk_fma_f32 v[98:99], v[110:111], v[82:83], v[98:99]
	v_pk_fma_f32 v[100:101], v[110:111], v[86:87], v[100:101]
	v_pk_fma_f32 v[174:175], v[110:111], v[90:91], v[174:175]
	v_pk_fma_f32 v[176:177], v[110:111], v[94:95], v[176:177]
	v_add_f32_e32 v140, v98, v99
	v_add_f32_e32 v141, v100, v101
	v_add_f32_e32 v142, v174, v175
	v_add_f32_e32 v144, v176, v177
	v_pk_mul_f32 v[98:99], v[108:109], v[84:85]
	v_pk_mul_f32 v[100:101], v[108:109], v[88:89]
	v_pk_mul_f32 v[174:175], v[108:109], v[92:93]
	v_pk_mul_f32 v[176:177], v[108:109], v[96:97]
	v_pk_fma_f32 v[98:99], v[106:107], v[82:83], v[98:99]
	v_pk_fma_f32 v[100:101], v[106:107], v[86:87], v[100:101]
	v_pk_fma_f32 v[174:175], v[106:107], v[90:91], v[174:175]
	v_pk_fma_f32 v[176:177], v[106:107], v[94:95], v[176:177]
	v_add_f32_e32 v147, v98, v99
	v_add_f32_e32 v148, v100, v101
	v_add_f32_e32 v149, v174, v175
	v_add_f32_e32 v150, v176, v177
	v_pk_mul_f32 v[98:99], v[104:105], v[84:85]
	v_pk_mul_f32 v[100:101], v[104:105], v[88:89]
	v_pk_mul_f32 v[174:175], v[104:105], v[92:93]
	v_pk_mul_f32 v[176:177], v[104:105], v[96:97]
	v_pk_fma_f32 v[98:99], v[102:103], v[82:83], v[98:99]
	v_pk_fma_f32 v[100:101], v[102:103], v[86:87], v[100:101]
	v_pk_fma_f32 v[174:175], v[102:103], v[90:91], v[174:175]
	v_pk_fma_f32 v[176:177], v[102:103], v[94:95], v[176:177]
	v_add_f32_e32 v151, v98, v99
	v_add_f32_e32 v152, v100, v101
	v_add_f32_e32 v153, v174, v175
	v_add_f32_e32 v154, v176, v177
	v_add_f32_e32 v155, v146, v172
	v_add_f32_e32 v156, v155, v145
	v_add_f32_e32 v157, v156, v143
	v_add_f32_dpp v136, v136, v136 row_mirror row_mask:0xf bank_mask:0x3 bound_ctrl:1
	v_add_f32_dpp v137, v137, v137 row_mirror row_mask:0xf bank_mask:0x3 bound_ctrl:1
	v_add_f32_dpp v138, v138, v138 row_mirror row_mask:0xf bank_mask:0x3 bound_ctrl:1
	v_add_f32_dpp v139, v139, v139 row_mirror row_mask:0xf bank_mask:0x3 bound_ctrl:1
	v_add_f32_dpp v140, v140, v140 row_mirror row_mask:0xf bank_mask:0x3 bound_ctrl:1
	v_add_f32_dpp v141, v141, v141 row_mirror row_mask:0xf bank_mask:0x3 bound_ctrl:1
	v_add_f32_dpp v142, v142, v142 row_mirror row_mask:0xf bank_mask:0x3 bound_ctrl:1
	v_add_f32_dpp v144, v144, v144 row_mirror row_mask:0xf bank_mask:0x3 bound_ctrl:1
	v_add_f32_dpp v136, v147, v147 row_mirror row_mask:0xf bank_mask:0xc bound_ctrl:1
	v_add_f32_dpp v137, v148, v148 row_mirror row_mask:0xf bank_mask:0xc bound_ctrl:1
	v_add_f32_dpp v138, v149, v149 row_mirror row_mask:0xf bank_mask:0xc bound_ctrl:1
	v_add_f32_dpp v139, v150, v150 row_mirror row_mask:0xf bank_mask:0xc bound_ctrl:1
	v_add_f32_dpp v140, v151, v151 row_mirror row_mask:0xf bank_mask:0xc bound_ctrl:1
	v_add_f32_dpp v141, v152, v152 row_mirror row_mask:0xf bank_mask:0xc bound_ctrl:1
	v_add_f32_dpp v142, v153, v153 row_mirror row_mask:0xf bank_mask:0xc bound_ctrl:1
	v_add_f32_dpp v144, v154, v154 row_mirror row_mask:0xf bank_mask:0xc bound_ctrl:1
	v_add_f32_dpp v136, v136, v136 row_half_mirror row_mask:0xf bank_mask:0x5 bound_ctrl:1
	v_add_f32_dpp v137, v137, v137 row_half_mirror row_mask:0xf bank_mask:0x5 bound_ctrl:1
	v_add_f32_dpp v138, v138, v138 row_half_mirror row_mask:0xf bank_mask:0x5 bound_ctrl:1
	v_add_f32_dpp v139, v139, v139 row_half_mirror row_mask:0xf bank_mask:0x5 bound_ctrl:1
	v_add_f32_dpp v136, v140, v140 row_half_mirror row_mask:0xf bank_mask:0xa bound_ctrl:1
	v_add_f32_dpp v137, v141, v141 row_half_mirror row_mask:0xf bank_mask:0xa bound_ctrl:1
	v_add_f32_dpp v138, v142, v142 row_half_mirror row_mask:0xf bank_mask:0xa bound_ctrl:1
	v_add_f32_dpp v139, v144, v144 row_half_mirror row_mask:0xf bank_mask:0xa bound_ctrl:1
	v_add_f32_dpp v136, v136, v136 quad_perm:[2,3,0,1] row_mask:0xf bank_mask:0xf bound_ctrl:1
	v_add_f32_dpp v138, v138, v138 quad_perm:[2,3,0,1] row_mask:0xf bank_mask:0xf bound_ctrl:1
	v_add_f32_dpp v137, v137, v137 quad_perm:[2,3,0,1] row_mask:0xf bank_mask:0xf bound_ctrl:1
	v_add_f32_dpp v139, v139, v139 quad_perm:[2,3,0,1] row_mask:0xf bank_mask:0xf bound_ctrl:1
	v_cndmask_b32_e64 v173, v155, v146, s[28:29]
	v_cndmask_b32_e64 v178, v157, v156, s[28:29]
	v_cndmask_b32_e64 v136, v136, v138, s[24:25]
	v_cndmask_b32_e64 v137, v137, v139, s[24:25]
	v_cndmask_b32_e64 v173, v178, v173, s[24:25]
	v_add_f32_e32 v146, v157, v163
	v_add_f32_dpp v136, v136, v136 quad_perm:[1,0,3,2] row_mask:0xf bank_mask:0xf bound_ctrl:1
	v_add_f32_dpp v137, v137, v137 quad_perm:[1,0,3,2] row_mask:0xf bank_mask:0xf bound_ctrl:1
	v_cndmask_b32_e64 v136, v136, v137, s[28:29]
	v_fmac_f32_e32 v136, 0x3fb8aa3b, v173
	s_nop 1
	v_max_f32_dpp v179, v136, v136 quad_perm:[1,0,3,2] row_mask:0xf bank_mask:0xf bound_ctrl:1
	s_nop 1
	v_max_f32_dpp v180, v179, v179 quad_perm:[2,3,0,1] row_mask:0xf bank_mask:0xf bound_ctrl:1
	v_max_f32_e32 v180, v134, v180
	v_sub_f32_e32 v155, v134, v180
	v_sub_f32_e32 v156, v136, v180
	v_mov_b32_e32 v134, v180
	v_exp_f32_e32 v155, v155
	v_exp_f32_e32 v156, v156
	s_nop 0
	v_mov_b32_dpp v137, v155 row_newbcast:0 row_mask:0xf bank_mask:0xf
	v_mov_b32_dpp v142, v155 row_newbcast:4 row_mask:0xf bank_mask:0xf
	v_mov_b32_dpp v150, v155 row_newbcast:8 row_mask:0xf bank_mask:0xf
	v_mov_b32_dpp v178, v155 row_newbcast:12 row_mask:0xf bank_mask:0xf
	v_add_f32_dpp v157, v156, v156 quad_perm:[1,0,3,2] row_mask:0xf bank_mask:0xf bound_ctrl:1
	v_mov_b32_dpp v138, v156 row_newbcast:0 row_mask:0xf bank_mask:0xf
	v_mov_b32_dpp v139, v156 row_newbcast:1 row_mask:0xf bank_mask:0xf
	v_mov_b32_dpp v140, v156 row_newbcast:2 row_mask:0xf bank_mask:0xf
	v_mov_b32_dpp v141, v156 row_newbcast:3 row_mask:0xf bank_mask:0xf
	v_add_f32_dpp v173, v157, v157 quad_perm:[2,3,0,1] row_mask:0xf bank_mask:0xf bound_ctrl:1
	v_mov_b32_dpp v144, v156 row_newbcast:4 row_mask:0xf bank_mask:0xf
	v_mov_b32_dpp v147, v156 row_newbcast:5 row_mask:0xf bank_mask:0xf
	v_mov_b32_dpp v148, v156 row_newbcast:6 row_mask:0xf bank_mask:0xf
	v_mov_b32_dpp v149, v156 row_newbcast:7 row_mask:0xf bank_mask:0xf
	v_fma_f32 v135, v135, v155, v173
	v_mov_b32_dpp v151, v156 row_newbcast:8 row_mask:0xf bank_mask:0xf
	v_mov_b32_dpp v152, v156 row_newbcast:9 row_mask:0xf bank_mask:0xf
	v_mov_b32_dpp v153, v156 row_newbcast:10 row_mask:0xf bank_mask:0xf
	v_mov_b32_dpp v154, v156 row_newbcast:11 row_mask:0xf bank_mask:0xf
	v_mov_b32_dpp v179, v156 row_newbcast:12 row_mask:0xf bank_mask:0xf
	v_mov_b32_dpp v180, v156 row_newbcast:13 row_mask:0xf bank_mask:0xf
	v_mov_b32_dpp v181, v156 row_newbcast:14 row_mask:0xf bank_mask:0xf
	v_mov_b32_dpp v0, v156 row_newbcast:15 row_mask:0xf bank_mask:0xf
	v_pk_mul_f32 v[118:119], v[118:119], v[136:137] op_sel:[0,1] op_sel_hi:[1,1]
	v_pk_mul_f32 v[120:121], v[120:121], v[136:137] op_sel:[0,1] op_sel_hi:[1,1]
	v_pk_mul_f32 v[122:123], v[122:123], v[142:143] op_sel:[0,0] op_sel_hi:[1,0]
	v_pk_mul_f32 v[124:125], v[124:125], v[142:143] op_sel:[0,0] op_sel_hi:[1,0]
	v_pk_mul_f32 v[126:127], v[126:127], v[150:151] op_sel:[0,0] op_sel_hi:[1,0]
	v_pk_mul_f32 v[128:129], v[128:129], v[150:151] op_sel:[0,0] op_sel_hi:[1,0]
	v_pk_mul_f32 v[130:131], v[130:131], v[178:179] op_sel:[0,0] op_sel_hi:[1,0]
	v_pk_mul_f32 v[132:133], v[132:133], v[178:179] op_sel:[0,0] op_sel_hi:[1,0]
	v_pk_fma_f32 v[118:119], v[138:139], v[66:67], v[118:119] op_sel:[0,0,0] op_sel_hi:[0,1,1]
	v_pk_fma_f32 v[120:121], v[138:139], v[68:69], v[120:121] op_sel:[0,0,0] op_sel_hi:[0,1,1]
	v_pk_fma_f32 v[122:123], v[144:145], v[66:67], v[122:123] op_sel:[0,0,0] op_sel_hi:[0,1,1]
	v_pk_fma_f32 v[124:125], v[144:145], v[68:69], v[124:125] op_sel:[0,0,0] op_sel_hi:[0,1,1]
	v_pk_fma_f32 v[126:127], v[150:151], v[66:67], v[126:127] op_sel:[1,0,0] op_sel_hi:[1,1,1]
	v_pk_fma_f32 v[128:129], v[150:151], v[68:69], v[128:129] op_sel:[1,0,0] op_sel_hi:[1,1,1]
	v_pk_fma_f32 v[130:131], v[178:179], v[66:67], v[130:131] op_sel:[1,0,0] op_sel_hi:[1,1,1]
	v_pk_fma_f32 v[132:133], v[178:179], v[68:69], v[132:133] op_sel:[1,0,0] op_sel_hi:[1,1,1]
	v_pk_fma_f32 v[118:119], v[138:139], v[70:71], v[118:119] op_sel:[1,0,0] op_sel_hi:[1,1,1]
	v_pk_fma_f32 v[120:121], v[138:139], v[72:73], v[120:121] op_sel:[1,0,0] op_sel_hi:[1,1,1]
	v_pk_fma_f32 v[122:123], v[146:147], v[70:71], v[122:123] op_sel:[1,0,0] op_sel_hi:[1,1,1]
	v_pk_fma_f32 v[124:125], v[146:147], v[72:73], v[124:125] op_sel:[1,0,0] op_sel_hi:[1,1,1]
	v_pk_fma_f32 v[126:127], v[152:153], v[70:71], v[126:127] op_sel:[0,0,0] op_sel_hi:[0,1,1]
	v_pk_fma_f32 v[128:129], v[152:153], v[72:73], v[128:129] op_sel:[0,0,0] op_sel_hi:[0,1,1]
	v_pk_fma_f32 v[130:131], v[180:181], v[70:71], v[130:131] op_sel:[0,0,0] op_sel_hi:[0,1,1]
	v_pk_fma_f32 v[132:133], v[180:181], v[72:73], v[132:133] op_sel:[0,0,0] op_sel_hi:[0,1,1]
	v_pk_fma_f32 v[118:119], v[140:141], v[74:75], v[118:119] op_sel:[0,0,0] op_sel_hi:[0,1,1]
	v_pk_fma_f32 v[120:121], v[140:141], v[76:77], v[120:121] op_sel:[0,0,0] op_sel_hi:[0,1,1]
	v_pk_fma_f32 v[122:123], v[148:149], v[74:75], v[122:123] op_sel:[0,0,0] op_sel_hi:[0,1,1]
	v_pk_fma_f32 v[124:125], v[148:149], v[76:77], v[124:125] op_sel:[0,0,0] op_sel_hi:[0,1,1]
	v_pk_fma_f32 v[126:127], v[152:153], v[74:75], v[126:127] op_sel:[1,0,0] op_sel_hi:[1,1,1]
	v_pk_fma_f32 v[128:129], v[152:153], v[76:77], v[128:129] op_sel:[1,0,0] op_sel_hi:[1,1,1]
	v_pk_fma_f32 v[130:131], v[180:181], v[74:75], v[130:131] op_sel:[1,0,0] op_sel_hi:[1,1,1]
	v_pk_fma_f32 v[132:133], v[180:181], v[76:77], v[132:133] op_sel:[1,0,0] op_sel_hi:[1,1,1]
	v_pk_fma_f32 v[118:119], v[140:141], v[78:79], v[118:119] op_sel:[1,0,0] op_sel_hi:[1,1,1]
	v_pk_fma_f32 v[120:121], v[140:141], v[80:81], v[120:121] op_sel:[1,0,0] op_sel_hi:[1,1,1]
	v_pk_fma_f32 v[122:123], v[148:149], v[78:79], v[122:123] op_sel:[1,0,0] op_sel_hi:[1,1,1]
	v_pk_fma_f32 v[124:125], v[148:149], v[80:81], v[124:125] op_sel:[1,0,0] op_sel_hi:[1,1,1]
	v_pk_fma_f32 v[126:127], v[154:155], v[78:79], v[126:127] op_sel:[0,0,0] op_sel_hi:[0,1,1]
	v_pk_fma_f32 v[128:129], v[154:155], v[80:81], v[128:129] op_sel:[0,0,0] op_sel_hi:[0,1,1]
	v_pk_fma_f32 v[130:131], v[0:1], v[78:79], v[130:131] op_sel:[0,0,0] op_sel_hi:[0,1,1]
	v_pk_fma_f32 v[132:133], v[0:1], v[80:81], v[132:133] op_sel:[0,0,0] op_sel_hi:[0,1,1]
	s_add_i32 s0, s8, 0x400
	buffer_load_dwordx4 v[82:85], v161, s[12:15], s8 offen nt
	buffer_load_dwordx4 v[66:69], v161, s[4:7], s8 offen nt
	buffer_load_dword v163, v162, s[16:19], s3 offen
	buffer_load_dwordx4 v[86:89], v161, s[12:15], s0 offen nt
	buffer_load_dwordx4 v[70:73], v161, s[4:7], s0 offen nt
	s_add_i32 s0, s3, 16
	buffer_load_dword v143, v162, s[16:19], s0 offen
	s_add_i32 s0, s8, 0x800
	buffer_load_dwordx4 v[90:93], v161, s[12:15], s0 offen nt
	buffer_load_dwordx4 v[74:77], v161, s[4:7], s0 offen nt
	s_add_i32 s0, s3, 32
	buffer_load_dword v145, v162, s[16:19], s0 offen
	s_add_i32 s0, s8, 0xc00
	buffer_load_dwordx4 v[94:97], v161, s[12:15], s0 offen nt
	buffer_load_dwordx4 v[78:81], v161, s[4:7], s0 offen nt
	s_add_i32 s0, s3, 48
	buffer_load_dword v172, v162, s[16:19], s0 offen
	s_add_i32 s2, s2, -12
	s_addk_i32 s3, 0xff40
	s_addk_i32 s8, 0xd000
	s_cmp_lt_u32 s2, 36
	s_cbranch_scc0 .Lpg_loop
	s_waitcnt vmcnt(24)
	v_pk_mul_f32 v[98:99], v[116:117], v[52:53]
	v_pk_mul_f32 v[100:101], v[116:117], v[60:61]
	v_pk_mul_f32 v[174:175], v[116:117], v[56:57]
	v_pk_mul_f32 v[176:177], v[116:117], v[64:65]
	v_pk_fma_f32 v[98:99], v[114:115], v[50:51], v[98:99]
	v_pk_fma_f32 v[100:101], v[114:115], v[58:59], v[100:101]
	v_pk_fma_f32 v[174:175], v[114:115], v[54:55], v[174:175]
	v_pk_fma_f32 v[176:177], v[114:115], v[62:63], v[176:177]
	v_add_f32_e32 v136, v98, v99
	v_add_f32_e32 v137, v100, v101
	v_add_f32_e32 v138, v174, v175
	v_add_f32_e32 v139, v176, v177
	v_pk_mul_f32 v[98:99], v[112:113], v[52:53]
	v_pk_mul_f32 v[100:101], v[112:113], v[60:61]
	v_pk_mul_f32 v[174:175], v[112:113], v[56:57]
	v_pk_mul_f32 v[176:177], v[112:113], v[64:65]
	v_pk_fma_f32 v[98:99], v[110:111], v[50:51], v[98:99]
	v_pk_fma_f32 v[100:101], v[110:111], v[58:59], v[100:101]
	v_pk_fma_f32 v[174:175], v[110:111], v[54:55], v[174:175]
	v_pk_fma_f32 v[176:177], v[110:111], v[62:63], v[176:177]
	v_add_f32_e32 v140, v98, v99
	v_add_f32_e32 v141, v100, v101
	v_add_f32_e32 v142, v174, v175
	v_add_f32_e32 v144, v176, v177
	v_pk_mul_f32 v[98:99], v[108:109], v[52:53]
	v_pk_mul_f32 v[100:101], v[108:109], v[60:61]
	v_pk_mul_f32 v[174:175], v[108:109], v[56:57]
	v_pk_mul_f32 v[176:177], v[108:109], v[64:65]
	v_pk_fma_f32 v[98:99], v[106:107], v[50:51], v[98:99]
	v_pk_fma_f32 v[100:101], v[106:107], v[58:59], v[100:101]
	v_pk_fma_f32 v[174:175], v[106:107], v[54:55], v[174:175]
	v_pk_fma_f32 v[176:177], v[106:107], v[62:63], v[176:177]
	v_add_f32_e32 v147, v98, v99
	v_add_f32_e32 v148, v100, v101
	v_add_f32_e32 v149, v174, v175
	v_add_f32_e32 v150, v176, v177
	v_pk_mul_f32 v[98:99], v[104:105], v[52:53]
	v_pk_mul_f32 v[100:101], v[104:105], v[60:61]
	v_pk_mul_f32 v[174:175], v[104:105], v[56:57]
	v_pk_mul_f32 v[176:177], v[104:105], v[64:65]
	v_pk_fma_f32 v[98:99], v[102:103], v[50:51], v[98:99]
	v_pk_fma_f32 v[100:101], v[102:103], v[58:59], v[100:101]
	v_pk_fma_f32 v[174:175], v[102:103], v[54:55], v[174:175]
	v_pk_fma_f32 v[176:177], v[102:103], v[62:63], v[176:177]
	v_add_f32_e32 v151, v98, v99
	v_add_f32_e32 v152, v100, v101
	v_add_f32_e32 v153, v174, v175
	v_add_f32_e32 v154, v176, v177
	v_add_f32_e32 v155, v146, v171
	v_add_f32_e32 v156, v155, v170
	v_add_f32_e32 v157, v156, v169
	v_add_f32_dpp v136, v136, v136 row_mirror row_mask:0xf bank_mask:0x3 bound_ctrl:1
	v_add_f32_dpp v137, v137, v137 row_mirror row_mask:0xf bank_mask:0x3 bound_ctrl:1
	v_add_f32_dpp v138, v138, v138 row_mirror row_mask:0xf bank_mask:0x3 bound_ctrl:1
	v_add_f32_dpp v139, v139, v139 row_mirror row_mask:0xf bank_mask:0x3 bound_ctrl:1
	v_add_f32_dpp v140, v140, v140 row_mirror row_mask:0xf bank_mask:0x3 bound_ctrl:1
	v_add_f32_dpp v141, v141, v141 row_mirror row_mask:0xf bank_mask:0x3 bound_ctrl:1
	v_add_f32_dpp v142, v142, v142 row_mirror row_mask:0xf bank_mask:0x3 bound_ctrl:1
	v_add_f32_dpp v144, v144, v144 row_mirror row_mask:0xf bank_mask:0x3 bound_ctrl:1
	v_add_f32_dpp v136, v147, v147 row_mirror row_mask:0xf bank_mask:0xc bound_ctrl:1
	v_add_f32_dpp v137, v148, v148 row_mirror row_mask:0xf bank_mask:0xc bound_ctrl:1
	v_add_f32_dpp v138, v149, v149 row_mirror row_mask:0xf bank_mask:0xc bound_ctrl:1
	v_add_f32_dpp v139, v150, v150 row_mirror row_mask:0xf bank_mask:0xc bound_ctrl:1
	v_add_f32_dpp v140, v151, v151 row_mirror row_mask:0xf bank_mask:0xc bound_ctrl:1
	v_add_f32_dpp v141, v152, v152 row_mirror row_mask:0xf bank_mask:0xc bound_ctrl:1
	v_add_f32_dpp v142, v153, v153 row_mirror row_mask:0xf bank_mask:0xc bound_ctrl:1
	v_add_f32_dpp v144, v154, v154 row_mirror row_mask:0xf bank_mask:0xc bound_ctrl:1
	v_add_f32_dpp v136, v136, v136 row_half_mirror row_mask:0xf bank_mask:0x5 bound_ctrl:1
	v_add_f32_dpp v137, v137, v137 row_half_mirror row_mask:0xf bank_mask:0x5 bound_ctrl:1
	v_add_f32_dpp v138, v138, v138 row_half_mirror row_mask:0xf bank_mask:0x5 bound_ctrl:1
	v_add_f32_dpp v139, v139, v139 row_half_mirror row_mask:0xf bank_mask:0x5 bound_ctrl:1
	v_add_f32_dpp v136, v140, v140 row_half_mirror row_mask:0xf bank_mask:0xa bound_ctrl:1
	v_add_f32_dpp v137, v141, v141 row_half_mirror row_mask:0xf bank_mask:0xa bound_ctrl:1
	v_add_f32_dpp v138, v142, v142 row_half_mirror row_mask:0xf bank_mask:0xa bound_ctrl:1
	v_add_f32_dpp v139, v144, v144 row_half_mirror row_mask:0xf bank_mask:0xa bound_ctrl:1
	v_add_f32_dpp v136, v136, v136 quad_perm:[2,3,0,1] row_mask:0xf bank_mask:0xf bound_ctrl:1
	v_add_f32_dpp v138, v138, v138 quad_perm:[2,3,0,1] row_mask:0xf bank_mask:0xf bound_ctrl:1
	v_add_f32_dpp v137, v137, v137 quad_perm:[2,3,0,1] row_mask:0xf bank_mask:0xf bound_ctrl:1
	v_add_f32_dpp v139, v139, v139 quad_perm:[2,3,0,1] row_mask:0xf bank_mask:0xf bound_ctrl:1
	v_cndmask_b32_e64 v173, v155, v146, s[28:29]
	v_cndmask_b32_e64 v178, v157, v156, s[28:29]
	v_cndmask_b32_e64 v136, v136, v138, s[24:25]
	v_cndmask_b32_e64 v137, v137, v139, s[24:25]
	v_cndmask_b32_e64 v173, v178, v173, s[24:25]
	v_add_f32_e32 v146, v157, v167
	v_add_f32_dpp v136, v136, v136 quad_perm:[1,0,3,2] row_mask:0xf bank_mask:0xf bound_ctrl:1
	v_add_f32_dpp v137, v137, v137 quad_perm:[1,0,3,2] row_mask:0xf bank_mask:0xf bound_ctrl:1
	v_cndmask_b32_e64 v136, v136, v137, s[28:29]
	v_fmac_f32_e32 v136, 0x3fb8aa3b, v173
	s_nop 1
	v_max_f32_dpp v179, v136, v136 quad_perm:[1,0,3,2] row_mask:0xf bank_mask:0xf bound_ctrl:1
	s_nop 1
	v_max_f32_dpp v180, v179, v179 quad_perm:[2,3,0,1] row_mask:0xf bank_mask:0xf bound_ctrl:1
	v_max_f32_e32 v180, v134, v180
	v_sub_f32_e32 v155, v134, v180
	v_sub_f32_e32 v156, v136, v180
	v_mov_b32_e32 v134, v180
	v_exp_f32_e32 v155, v155
	v_exp_f32_e32 v156, v156
	s_nop 0
	v_mov_b32_dpp v137, v155 row_newbcast:0 row_mask:0xf bank_mask:0xf
	v_mov_b32_dpp v142, v155 row_newbcast:4 row_mask:0xf bank_mask:0xf
	v_mov_b32_dpp v150, v155 row_newbcast:8 row_mask:0xf bank_mask:0xf
	v_mov_b32_dpp v178, v155 row_newbcast:12 row_mask:0xf bank_mask:0xf
	v_add_f32_dpp v157, v156, v156 quad_perm:[1,0,3,2] row_mask:0xf bank_mask:0xf bound_ctrl:1
	v_mov_b32_dpp v138, v156 row_newbcast:0 row_mask:0xf bank_mask:0xf
	v_mov_b32_dpp v139, v156 row_newbcast:1 row_mask:0xf bank_mask:0xf
	v_mov_b32_dpp v140, v156 row_newbcast:2 row_mask:0xf bank_mask:0xf
	v_mov_b32_dpp v141, v156 row_newbcast:3 row_mask:0xf bank_mask:0xf
	v_add_f32_dpp v173, v157, v157 quad_perm:[2,3,0,1] row_mask:0xf bank_mask:0xf bound_ctrl:1
	v_mov_b32_dpp v144, v156 row_newbcast:4 row_mask:0xf bank_mask:0xf
	v_mov_b32_dpp v147, v156 row_newbcast:5 row_mask:0xf bank_mask:0xf
	v_mov_b32_dpp v148, v156 row_newbcast:6 row_mask:0xf bank_mask:0xf
	v_mov_b32_dpp v149, v156 row_newbcast:7 row_mask:0xf bank_mask:0xf
	v_fma_f32 v135, v135, v155, v173
	v_mov_b32_dpp v151, v156 row_newbcast:8 row_mask:0xf bank_mask:0xf
	v_mov_b32_dpp v152, v156 row_newbcast:9 row_mask:0xf bank_mask:0xf
	v_mov_b32_dpp v153, v156 row_newbcast:10 row_mask:0xf bank_mask:0xf
	v_mov_b32_dpp v154, v156 row_newbcast:11 row_mask:0xf bank_mask:0xf
	v_mov_b32_dpp v179, v156 row_newbcast:12 row_mask:0xf bank_mask:0xf
	v_mov_b32_dpp v180, v156 row_newbcast:13 row_mask:0xf bank_mask:0xf
	v_mov_b32_dpp v181, v156 row_newbcast:14 row_mask:0xf bank_mask:0xf
	v_mov_b32_dpp v0, v156 row_newbcast:15 row_mask:0xf bank_mask:0xf
	v_pk_mul_f32 v[118:119], v[118:119], v[136:137] op_sel:[0,1] op_sel_hi:[1,1]
	v_pk_mul_f32 v[120:121], v[120:121], v[136:137] op_sel:[0,1] op_sel_hi:[1,1]
	v_pk_mul_f32 v[122:123], v[122:123], v[142:143] op_sel:[0,0] op_sel_hi:[1,0]
	v_pk_mul_f32 v[124:125], v[124:125], v[142:143] op_sel:[0,0] op_sel_hi:[1,0]
	v_pk_mul_f32 v[126:127], v[126:127], v[150:151] op_sel:[0,0] op_sel_hi:[1,0]
	v_pk_mul_f32 v[128:129], v[128:129], v[150:151] op_sel:[0,0] op_sel_hi:[1,0]
	v_pk_mul_f32 v[130:131], v[130:131], v[178:179] op_sel:[0,0] op_sel_hi:[1,0]
	v_pk_mul_f32 v[132:133], v[132:133], v[178:179] op_sel:[0,0] op_sel_hi:[1,0]
	v_pk_fma_f32 v[118:119], v[138:139], v[22:23], v[118:119] op_sel:[0,0,0] op_sel_hi:[0,1,1]
	v_pk_fma_f32 v[120:121], v[138:139], v[24:25], v[120:121] op_sel:[0,0,0] op_sel_hi:[0,1,1]
	v_pk_fma_f32 v[122:123], v[144:145], v[22:23], v[122:123] op_sel:[0,0,0] op_sel_hi:[0,1,1]
	v_pk_fma_f32 v[124:125], v[144:145], v[24:25], v[124:125] op_sel:[0,0,0] op_sel_hi:[0,1,1]
	v_pk_fma_f32 v[126:127], v[150:151], v[22:23], v[126:127] op_sel:[1,0,0] op_sel_hi:[1,1,1]
	v_pk_fma_f32 v[128:129], v[150:151], v[24:25], v[128:129] op_sel:[1,0,0] op_sel_hi:[1,1,1]
	v_pk_fma_f32 v[130:131], v[178:179], v[22:23], v[130:131] op_sel:[1,0,0] op_sel_hi:[1,1,1]
	v_pk_fma_f32 v[132:133], v[178:179], v[24:25], v[132:133] op_sel:[1,0,0] op_sel_hi:[1,1,1]
	v_pk_fma_f32 v[118:119], v[138:139], v[18:19], v[118:119] op_sel:[1,0,0] op_sel_hi:[1,1,1]
	v_pk_fma_f32 v[120:121], v[138:139], v[20:21], v[120:121] op_sel:[1,0,0] op_sel_hi:[1,1,1]
	v_pk_fma_f32 v[122:123], v[146:147], v[18:19], v[122:123] op_sel:[1,0,0] op_sel_hi:[1,1,1]
	v_pk_fma_f32 v[124:125], v[146:147], v[20:21], v[124:125] op_sel:[1,0,0] op_sel_hi:[1,1,1]
	v_pk_fma_f32 v[126:127], v[152:153], v[18:19], v[126:127] op_sel:[0,0,0] op_sel_hi:[0,1,1]
	v_pk_fma_f32 v[128:129], v[152:153], v[20:21], v[128:129] op_sel:[0,0,0] op_sel_hi:[0,1,1]
	v_pk_fma_f32 v[130:131], v[180:181], v[18:19], v[130:131] op_sel:[0,0,0] op_sel_hi:[0,1,1]
	v_pk_fma_f32 v[132:133], v[180:181], v[20:21], v[132:133] op_sel:[0,0,0] op_sel_hi:[0,1,1]
	v_pk_fma_f32 v[118:119], v[140:141], v[26:27], v[118:119] op_sel:[0,0,0] op_sel_hi:[0,1,1]
	v_pk_fma_f32 v[120:121], v[140:141], v[28:29], v[120:121] op_sel:[0,0,0] op_sel_hi:[0,1,1]
	v_pk_fma_f32 v[122:123], v[148:149], v[26:27], v[122:123] op_sel:[0,0,0] op_sel_hi:[0,1,1]
	v_pk_fma_f32 v[124:125], v[148:149], v[28:29], v[124:125] op_sel:[0,0,0] op_sel_hi:[0,1,1]
	v_pk_fma_f32 v[126:127], v[152:153], v[26:27], v[126:127] op_sel:[1,0,0] op_sel_hi:[1,1,1]
	v_pk_fma_f32 v[128:129], v[152:153], v[28:29], v[128:129] op_sel:[1,0,0] op_sel_hi:[1,1,1]
	v_pk_fma_f32 v[130:131], v[180:181], v[26:27], v[130:131] op_sel:[1,0,0] op_sel_hi:[1,1,1]
	v_pk_fma_f32 v[132:133], v[180:181], v[28:29], v[132:133] op_sel:[1,0,0] op_sel_hi:[1,1,1]
	v_pk_fma_f32 v[118:119], v[140:141], v[30:31], v[118:119] op_sel:[1,0,0] op_sel_hi:[1,1,1]
	v_pk_fma_f32 v[120:121], v[140:141], v[32:33], v[120:121] op_sel:[1,0,0] op_sel_hi:[1,1,1]
	v_pk_fma_f32 v[122:123], v[148:149], v[30:31], v[122:123] op_sel:[1,0,0] op_sel_hi:[1,1,1]
	v_pk_fma_f32 v[124:125], v[148:149], v[32:33], v[124:125] op_sel:[1,0,0] op_sel_hi:[1,1,1]
	v_pk_fma_f32 v[126:127], v[154:155], v[30:31], v[126:127] op_sel:[0,0,0] op_sel_hi:[0,1,1]
	v_pk_fma_f32 v[128:129], v[154:155], v[32:33], v[128:129] op_sel:[0,0,0] op_sel_hi:[0,1,1]
	v_pk_fma_f32 v[130:131], v[0:1], v[30:31], v[130:131] op_sel:[0,0,0] op_sel_hi:[0,1,1]
	v_pk_fma_f32 v[132:133], v[0:1], v[32:33], v[132:133] op_sel:[0,0,0] op_sel_hi:[0,1,1]
	s_add_i32 s0, s8, 0x2000
	s_mov_b32 s6, s14
	s_mov_b32 s7, s15
	buffer_load_dwordx4 v[50:53], v161, s[12:15], s0 offen nt
	buffer_load_dwordx4 v[22:25], v161, s[4:7], s0 offen nt
	s_add_i32 s0, s3, 0x80
	buffer_load_dword v167, v162, s[16:19], s0 offen
	s_add_i32 s0, s8, 0x2400
	buffer_load_dwordx4 v[58:61], v161, s[12:15], s0 offen nt
	buffer_load_dwordx4 v[18:21], v161, s[4:7], s0 offen nt
	s_add_i32 s0, s3, 0x90
	buffer_load_dword v169, v162, s[16:19], s0 offen
	s_add_i32 s0, s8, 0x2800
	buffer_load_dwordx4 v[54:57], v161, s[12:15], s0 offen nt
	buffer_load_dwordx4 v[26:29], v161, s[4:7], s0 offen nt
	s_add_i32 s0, s3, 0xa0
	buffer_load_dword v170, v162, s[16:19], s0 offen
	s_add_i32 s0, s8, 0x2c00
	buffer_load_dwordx4 v[62:65], v161, s[12:15], s0 offen nt
	buffer_load_dwordx4 v[30:33], v161, s[4:7], s0 offen nt
	s_add_i32 s0, s3, 0xb0
	buffer_load_dword v171, v162, s[16:19], s0 offen
	s_waitcnt vmcnt(24)
	v_pk_mul_f32 v[98:99], v[116:117], v[36:37]
	v_pk_mul_f32 v[100:101], v[116:117], v[44:45]
	v_pk_mul_f32 v[174:175], v[116:117], v[40:41]
	v_pk_mul_f32 v[176:177], v[116:117], v[48:49]
	v_pk_fma_f32 v[98:99], v[114:115], v[34:35], v[98:99]
	v_pk_fma_f32 v[100:101], v[114:115], v[42:43], v[100:101]
	v_pk_fma_f32 v[174:175], v[114:115], v[38:39], v[174:175]
	v_pk_fma_f32 v[176:177], v[114:115], v[46:47], v[176:177]
	v_add_f32_e32 v136, v98, v99
	v_add_f32_e32 v137, v100, v101
	v_add_f32_e32 v138, v174, v175
	v_add_f32_e32 v139, v176, v177
	v_pk_mul_f32 v[98:99], v[112:113], v[36:37]
	v_pk_mul_f32 v[100:101], v[112:113], v[44:45]
	v_pk_mul_f32 v[174:175], v[112:113], v[40:41]
	v_pk_mul_f32 v[176:177], v[112:113], v[48:49]
	v_pk_fma_f32 v[98:99], v[110:111], v[34:35], v[98:99]
	v_pk_fma_f32 v[100:101], v[110:111], v[42:43], v[100:101]
	v_pk_fma_f32 v[174:175], v[110:111], v[38:39], v[174:175]
	v_pk_fma_f32 v[176:177], v[110:111], v[46:47], v[176:177]
	v_add_f32_e32 v140, v98, v99
	v_add_f32_e32 v141, v100, v101
	v_add_f32_e32 v142, v174, v175
	v_add_f32_e32 v144, v176, v177
	v_pk_mul_f32 v[98:99], v[108:109], v[36:37]
	v_pk_mul_f32 v[100:101], v[108:109], v[44:45]
	v_pk_mul_f32 v[174:175], v[108:109], v[40:41]
	v_pk_mul_f32 v[176:177], v[108:109], v[48:49]
	v_pk_fma_f32 v[98:99], v[106:107], v[34:35], v[98:99]
	v_pk_fma_f32 v[100:101], v[106:107], v[42:43], v[100:101]
	v_pk_fma_f32 v[174:175], v[106:107], v[38:39], v[174:175]
	v_pk_fma_f32 v[176:177], v[106:107], v[46:47], v[176:177]
	v_add_f32_e32 v147, v98, v99
	v_add_f32_e32 v148, v100, v101
	v_add_f32_e32 v149, v174, v175
	v_add_f32_e32 v150, v176, v177
	v_pk_mul_f32 v[98:99], v[104:105], v[36:37]
	v_pk_mul_f32 v[100:101], v[104:105], v[44:45]
	v_pk_mul_f32 v[174:175], v[104:105], v[40:41]
	v_pk_mul_f32 v[176:177], v[104:105], v[48:49]
	v_pk_fma_f32 v[98:99], v[102:103], v[34:35], v[98:99]
	v_pk_fma_f32 v[100:101], v[102:103], v[42:43], v[100:101]
	v_pk_fma_f32 v[174:175], v[102:103], v[38:39], v[174:175]
	v_pk_fma_f32 v[176:177], v[102:103], v[46:47], v[176:177]
	v_add_f32_e32 v151, v98, v99
	v_add_f32_e32 v152, v100, v101
	v_add_f32_e32 v153, v174, v175
	v_add_f32_e32 v154, v176, v177
	v_add_f32_e32 v155, v146, v166
	v_add_f32_e32 v156, v155, v165
	v_add_f32_e32 v157, v156, v164
	v_add_f32_dpp v136, v136, v136 row_mirror row_mask:0xf bank_mask:0x3 bound_ctrl:1
	v_add_f32_dpp v137, v137, v137 row_mirror row_mask:0xf bank_mask:0x3 bound_ctrl:1
	v_add_f32_dpp v138, v138, v138 row_mirror row_mask:0xf bank_mask:0x3 bound_ctrl:1
	v_add_f32_dpp v139, v139, v139 row_mirror row_mask:0xf bank_mask:0x3 bound_ctrl:1
	v_add_f32_dpp v140, v140, v140 row_mirror row_mask:0xf bank_mask:0x3 bound_ctrl:1
	v_add_f32_dpp v141, v141, v141 row_mirror row_mask:0xf bank_mask:0x3 bound_ctrl:1
	v_add_f32_dpp v142, v142, v142 row_mirror row_mask:0xf bank_mask:0x3 bound_ctrl:1
	v_add_f32_dpp v144, v144, v144 row_mirror row_mask:0xf bank_mask:0x3 bound_ctrl:1
	v_add_f32_dpp v136, v147, v147 row_mirror row_mask:0xf bank_mask:0xc bound_ctrl:1
	v_add_f32_dpp v137, v148, v148 row_mirror row_mask:0xf bank_mask:0xc bound_ctrl:1
	v_add_f32_dpp v138, v149, v149 row_mirror row_mask:0xf bank_mask:0xc bound_ctrl:1
	v_add_f32_dpp v139, v150, v150 row_mirror row_mask:0xf bank_mask:0xc bound_ctrl:1
	v_add_f32_dpp v140, v151, v151 row_mirror row_mask:0xf bank_mask:0xc bound_ctrl:1
	v_add_f32_dpp v141, v152, v152 row_mirror row_mask:0xf bank_mask:0xc bound_ctrl:1
	v_add_f32_dpp v142, v153, v153 row_mirror row_mask:0xf bank_mask:0xc bound_ctrl:1
	v_add_f32_dpp v144, v154, v154 row_mirror row_mask:0xf bank_mask:0xc bound_ctrl:1
	v_add_f32_dpp v136, v136, v136 row_half_mirror row_mask:0xf bank_mask:0x5 bound_ctrl:1
	v_add_f32_dpp v137, v137, v137 row_half_mirror row_mask:0xf bank_mask:0x5 bound_ctrl:1
	v_add_f32_dpp v138, v138, v138 row_half_mirror row_mask:0xf bank_mask:0x5 bound_ctrl:1
	v_add_f32_dpp v139, v139, v139 row_half_mirror row_mask:0xf bank_mask:0x5 bound_ctrl:1
	v_add_f32_dpp v136, v140, v140 row_half_mirror row_mask:0xf bank_mask:0xa bound_ctrl:1
	v_add_f32_dpp v137, v141, v141 row_half_mirror row_mask:0xf bank_mask:0xa bound_ctrl:1
	v_add_f32_dpp v138, v142, v142 row_half_mirror row_mask:0xf bank_mask:0xa bound_ctrl:1
	v_add_f32_dpp v139, v144, v144 row_half_mirror row_mask:0xf bank_mask:0xa bound_ctrl:1
	v_add_f32_dpp v136, v136, v136 quad_perm:[2,3,0,1] row_mask:0xf bank_mask:0xf bound_ctrl:1
	v_add_f32_dpp v138, v138, v138 quad_perm:[2,3,0,1] row_mask:0xf bank_mask:0xf bound_ctrl:1
	v_add_f32_dpp v137, v137, v137 quad_perm:[2,3,0,1] row_mask:0xf bank_mask:0xf bound_ctrl:1
	v_add_f32_dpp v139, v139, v139 quad_perm:[2,3,0,1] row_mask:0xf bank_mask:0xf bound_ctrl:1
	v_cndmask_b32_e64 v173, v155, v146, s[28:29]
	v_cndmask_b32_e64 v178, v157, v156, s[28:29]
	v_cndmask_b32_e64 v136, v136, v138, s[24:25]
	v_cndmask_b32_e64 v137, v137, v139, s[24:25]
	v_cndmask_b32_e64 v173, v178, v173, s[24:25]
	v_add_f32_e32 v146, v157, v168
	v_add_f32_dpp v136, v136, v136 quad_perm:[1,0,3,2] row_mask:0xf bank_mask:0xf bound_ctrl:1
	v_add_f32_dpp v137, v137, v137 quad_perm:[1,0,3,2] row_mask:0xf bank_mask:0xf bound_ctrl:1
	v_cndmask_b32_e64 v136, v136, v137, s[28:29]
	v_fmac_f32_e32 v136, 0x3fb8aa3b, v173
	s_nop 1
	v_max_f32_dpp v179, v136, v136 quad_perm:[1,0,3,2] row_mask:0xf bank_mask:0xf bound_ctrl:1
	s_nop 1
	v_max_f32_dpp v180, v179, v179 quad_perm:[2,3,0,1] row_mask:0xf bank_mask:0xf bound_ctrl:1
	v_max_f32_e32 v180, v134, v180
	v_sub_f32_e32 v155, v134, v180
	v_sub_f32_e32 v156, v136, v180
	v_mov_b32_e32 v134, v180
	v_exp_f32_e32 v155, v155
	v_exp_f32_e32 v156, v156
	s_nop 0
	v_mov_b32_dpp v137, v155 row_newbcast:0 row_mask:0xf bank_mask:0xf
	v_mov_b32_dpp v142, v155 row_newbcast:4 row_mask:0xf bank_mask:0xf
	v_mov_b32_dpp v150, v155 row_newbcast:8 row_mask:0xf bank_mask:0xf
	v_mov_b32_dpp v178, v155 row_newbcast:12 row_mask:0xf bank_mask:0xf
	v_add_f32_dpp v157, v156, v156 quad_perm:[1,0,3,2] row_mask:0xf bank_mask:0xf bound_ctrl:1
	v_mov_b32_dpp v138, v156 row_newbcast:0 row_mask:0xf bank_mask:0xf
	v_mov_b32_dpp v139, v156 row_newbcast:1 row_mask:0xf bank_mask:0xf
	v_mov_b32_dpp v140, v156 row_newbcast:2 row_mask:0xf bank_mask:0xf
	v_mov_b32_dpp v141, v156 row_newbcast:3 row_mask:0xf bank_mask:0xf
	v_add_f32_dpp v173, v157, v157 quad_perm:[2,3,0,1] row_mask:0xf bank_mask:0xf bound_ctrl:1
	v_mov_b32_dpp v144, v156 row_newbcast:4 row_mask:0xf bank_mask:0xf
	v_mov_b32_dpp v147, v156 row_newbcast:5 row_mask:0xf bank_mask:0xf
	v_mov_b32_dpp v148, v156 row_newbcast:6 row_mask:0xf bank_mask:0xf
	v_mov_b32_dpp v149, v156 row_newbcast:7 row_mask:0xf bank_mask:0xf
	v_fma_f32 v135, v135, v155, v173
	v_mov_b32_dpp v151, v156 row_newbcast:8 row_mask:0xf bank_mask:0xf
	v_mov_b32_dpp v152, v156 row_newbcast:9 row_mask:0xf bank_mask:0xf
	v_mov_b32_dpp v153, v156 row_newbcast:10 row_mask:0xf bank_mask:0xf
	v_mov_b32_dpp v154, v156 row_newbcast:11 row_mask:0xf bank_mask:0xf
	v_mov_b32_dpp v179, v156 row_newbcast:12 row_mask:0xf bank_mask:0xf
	v_mov_b32_dpp v180, v156 row_newbcast:13 row_mask:0xf bank_mask:0xf
	v_mov_b32_dpp v181, v156 row_newbcast:14 row_mask:0xf bank_mask:0xf
	v_mov_b32_dpp v0, v156 row_newbcast:15 row_mask:0xf bank_mask:0xf
	v_pk_mul_f32 v[118:119], v[118:119], v[136:137] op_sel:[0,1] op_sel_hi:[1,1]
	v_pk_mul_f32 v[120:121], v[120:121], v[136:137] op_sel:[0,1] op_sel_hi:[1,1]
	v_pk_mul_f32 v[122:123], v[122:123], v[142:143] op_sel:[0,0] op_sel_hi:[1,0]
	v_pk_mul_f32 v[124:125], v[124:125], v[142:143] op_sel:[0,0] op_sel_hi:[1,0]
	v_pk_mul_f32 v[126:127], v[126:127], v[150:151] op_sel:[0,0] op_sel_hi:[1,0]
	v_pk_mul_f32 v[128:129], v[128:129], v[150:151] op_sel:[0,0] op_sel_hi:[1,0]
	v_pk_mul_f32 v[130:131], v[130:131], v[178:179] op_sel:[0,0] op_sel_hi:[1,0]
	v_pk_mul_f32 v[132:133], v[132:133], v[178:179] op_sel:[0,0] op_sel_hi:[1,0]
	v_pk_fma_f32 v[118:119], v[138:139], v[2:3], v[118:119] op_sel:[0,0,0] op_sel_hi:[0,1,1]
	v_pk_fma_f32 v[120:121], v[138:139], v[4:5], v[120:121] op_sel:[0,0,0] op_sel_hi:[0,1,1]
	v_pk_fma_f32 v[122:123], v[144:145], v[2:3], v[122:123] op_sel:[0,0,0] op_sel_hi:[0,1,1]
	v_pk_fma_f32 v[124:125], v[144:145], v[4:5], v[124:125] op_sel:[0,0,0] op_sel_hi:[0,1,1]
	v_pk_fma_f32 v[126:127], v[150:151], v[2:3], v[126:127] op_sel:[1,0,0] op_sel_hi:[1,1,1]
	v_pk_fma_f32 v[128:129], v[150:151], v[4:5], v[128:129] op_sel:[1,0,0] op_sel_hi:[1,1,1]
	v_pk_fma_f32 v[130:131], v[178:179], v[2:3], v[130:131] op_sel:[1,0,0] op_sel_hi:[1,1,1]
	v_pk_fma_f32 v[132:133], v[178:179], v[4:5], v[132:133] op_sel:[1,0,0] op_sel_hi:[1,1,1]
	v_pk_fma_f32 v[118:119], v[138:139], v[6:7], v[118:119] op_sel:[1,0,0] op_sel_hi:[1,1,1]
	v_pk_fma_f32 v[120:121], v[138:139], v[8:9], v[120:121] op_sel:[1,0,0] op_sel_hi:[1,1,1]
	v_pk_fma_f32 v[122:123], v[146:147], v[6:7], v[122:123] op_sel:[1,0,0] op_sel_hi:[1,1,1]
	v_pk_fma_f32 v[124:125], v[146:147], v[8:9], v[124:125] op_sel:[1,0,0] op_sel_hi:[1,1,1]
	v_pk_fma_f32 v[126:127], v[152:153], v[6:7], v[126:127] op_sel:[0,0,0] op_sel_hi:[0,1,1]
	v_pk_fma_f32 v[128:129], v[152:153], v[8:9], v[128:129] op_sel:[0,0,0] op_sel_hi:[0,1,1]
	v_pk_fma_f32 v[130:131], v[180:181], v[6:7], v[130:131] op_sel:[0,0,0] op_sel_hi:[0,1,1]
	v_pk_fma_f32 v[132:133], v[180:181], v[8:9], v[132:133] op_sel:[0,0,0] op_sel_hi:[0,1,1]
	v_pk_fma_f32 v[118:119], v[140:141], v[10:11], v[118:119] op_sel:[0,0,0] op_sel_hi:[0,1,1]
	v_pk_fma_f32 v[120:121], v[140:141], v[12:13], v[120:121] op_sel:[0,0,0] op_sel_hi:[0,1,1]
	v_pk_fma_f32 v[122:123], v[148:149], v[10:11], v[122:123] op_sel:[0,0,0] op_sel_hi:[0,1,1]
	v_pk_fma_f32 v[124:125], v[148:149], v[12:13], v[124:125] op_sel:[0,0,0] op_sel_hi:[0,1,1]
	v_pk_fma_f32 v[126:127], v[152:153], v[10:11], v[126:127] op_sel:[1,0,0] op_sel_hi:[1,1,1]
	v_pk_fma_f32 v[128:129], v[152:153], v[12:13], v[128:129] op_sel:[1,0,0] op_sel_hi:[1,1,1]
	v_pk_fma_f32 v[130:131], v[180:181], v[10:11], v[130:131] op_sel:[1,0,0] op_sel_hi:[1,1,1]
	v_pk_fma_f32 v[132:133], v[180:181], v[12:13], v[132:133] op_sel:[1,0,0] op_sel_hi:[1,1,1]
	v_pk_fma_f32 v[118:119], v[140:141], v[14:15], v[118:119] op_sel:[1,0,0] op_sel_hi:[1,1,1]
	v_pk_fma_f32 v[120:121], v[140:141], v[16:17], v[120:121] op_sel:[1,0,0] op_sel_hi:[1,1,1]
	v_pk_fma_f32 v[122:123], v[148:149], v[14:15], v[122:123] op_sel:[1,0,0] op_sel_hi:[1,1,1]
	v_pk_fma_f32 v[124:125], v[148:149], v[16:17], v[124:125] op_sel:[1,0,0] op_sel_hi:[1,1,1]
	v_pk_fma_f32 v[126:127], v[154:155], v[14:15], v[126:127] op_sel:[0,0,0] op_sel_hi:[0,1,1]
	v_pk_fma_f32 v[128:129], v[154:155], v[16:17], v[128:129] op_sel:[0,0,0] op_sel_hi:[0,1,1]
	v_pk_fma_f32 v[130:131], v[0:1], v[14:15], v[130:131] op_sel:[0,0,0] op_sel_hi:[0,1,1]
	v_pk_fma_f32 v[132:133], v[0:1], v[16:17], v[132:133] op_sel:[0,0,0] op_sel_hi:[0,1,1]
	s_add_i32 s0, s8, 0x1000
	buffer_load_dwordx4 v[34:37], v161, s[12:15], s0 offen nt
	buffer_load_dwordx4 v[2:5], v161, s[4:7], s0 offen nt
	s_add_i32 s0, s3, 64
	buffer_load_dword v168, v162, s[16:19], s0 offen
	s_add_i32 s0, s8, 0x1400
	buffer_load_dwordx4 v[42:45], v161, s[12:15], s0 offen nt
	buffer_load_dwordx4 v[6:9], v161, s[4:7], s0 offen nt
	s_add_i32 s0, s3, 0x50
	buffer_load_dword v164, v162, s[16:19], s0 offen
	s_add_i32 s0, s8, 0x1800
	buffer_load_dwordx4 v[38:41], v161, s[12:15], s0 offen nt
	buffer_load_dwordx4 v[10:13], v161, s[4:7], s0 offen nt
	s_add_i32 s0, s3, 0x60
	buffer_load_dword v165, v162, s[16:19], s0 offen
	s_add_i32 s0, s8, 0x1c00
	buffer_load_dwordx4 v[46:49], v161, s[12:15], s0 offen nt
	buffer_load_dwordx4 v[14:17], v161, s[4:7], s0 offen nt
	s_add_i32 s0, s3, 0x70
	buffer_load_dword v166, v162, s[16:19], s0 offen
	s_waitcnt vmcnt(24)
	v_pk_mul_f32 v[98:99], v[116:117], v[84:85]
	v_pk_mul_f32 v[100:101], v[116:117], v[88:89]
	v_pk_mul_f32 v[174:175], v[116:117], v[92:93]
	v_pk_mul_f32 v[176:177], v[116:117], v[96:97]
	v_pk_fma_f32 v[98:99], v[114:115], v[82:83], v[98:99]
	v_pk_fma_f32 v[100:101], v[114:115], v[86:87], v[100:101]
	v_pk_fma_f32 v[174:175], v[114:115], v[90:91], v[174:175]
	v_pk_fma_f32 v[176:177], v[114:115], v[94:95], v[176:177]
	v_add_f32_e32 v136, v98, v99
	v_add_f32_e32 v137, v100, v101
	v_add_f32_e32 v138, v174, v175
	v_add_f32_e32 v139, v176, v177
	v_pk_mul_f32 v[98:99], v[112:113], v[84:85]
	v_pk_mul_f32 v[100:101], v[112:113], v[88:89]
	v_pk_mul_f32 v[174:175], v[112:113], v[92:93]
	v_pk_mul_f32 v[176:177], v[112:113], v[96:97]
	v_pk_fma_f32 v[98:99], v[110:111], v[82:83], v[98:99]
	v_pk_fma_f32 v[100:101], v[110:111], v[86:87], v[100:101]
	v_pk_fma_f32 v[174:175], v[110:111], v[90:91], v[174:175]
	v_pk_fma_f32 v[176:177], v[110:111], v[94:95], v[176:177]
	v_add_f32_e32 v140, v98, v99
	v_add_f32_e32 v141, v100, v101
	v_add_f32_e32 v142, v174, v175
	v_add_f32_e32 v144, v176, v177
	v_pk_mul_f32 v[98:99], v[108:109], v[84:85]
	v_pk_mul_f32 v[100:101], v[108:109], v[88:89]
	v_pk_mul_f32 v[174:175], v[108:109], v[92:93]
	v_pk_mul_f32 v[176:177], v[108:109], v[96:97]
	v_pk_fma_f32 v[98:99], v[106:107], v[82:83], v[98:99]
	v_pk_fma_f32 v[100:101], v[106:107], v[86:87], v[100:101]
	v_pk_fma_f32 v[174:175], v[106:107], v[90:91], v[174:175]
	v_pk_fma_f32 v[176:177], v[106:107], v[94:95], v[176:177]
	v_add_f32_e32 v147, v98, v99
	v_add_f32_e32 v148, v100, v101
	v_add_f32_e32 v149, v174, v175
	v_add_f32_e32 v150, v176, v177
	v_pk_mul_f32 v[98:99], v[104:105], v[84:85]
	v_pk_mul_f32 v[100:101], v[104:105], v[88:89]
	v_pk_mul_f32 v[174:175], v[104:105], v[92:93]
	v_pk_mul_f32 v[176:177], v[104:105], v[96:97]
	v_pk_fma_f32 v[98:99], v[102:103], v[82:83], v[98:99]
	v_pk_fma_f32 v[100:101], v[102:103], v[86:87], v[100:101]
	v_pk_fma_f32 v[174:175], v[102:103], v[90:91], v[174:175]
	v_pk_fma_f32 v[176:177], v[102:103], v[94:95], v[176:177]
	v_add_f32_e32 v151, v98, v99
	v_add_f32_e32 v152, v100, v101
	v_add_f32_e32 v153, v174, v175
	v_add_f32_e32 v154, v176, v177
	v_add_f32_e32 v155, v146, v172
	v_add_f32_e32 v156, v155, v145
	v_add_f32_e32 v157, v156, v143
	v_add_f32_dpp v136, v136, v136 row_mirror row_mask:0xf bank_mask:0x3 bound_ctrl:1
	v_add_f32_dpp v137, v137, v137 row_mirror row_mask:0xf bank_mask:0x3 bound_ctrl:1
	v_add_f32_dpp v138, v138, v138 row_mirror row_mask:0xf bank_mask:0x3 bound_ctrl:1
	v_add_f32_dpp v139, v139, v139 row_mirror row_mask:0xf bank_mask:0x3 bound_ctrl:1
	v_add_f32_dpp v140, v140, v140 row_mirror row_mask:0xf bank_mask:0x3 bound_ctrl:1
	v_add_f32_dpp v141, v141, v141 row_mirror row_mask:0xf bank_mask:0x3 bound_ctrl:1
	v_add_f32_dpp v142, v142, v142 row_mirror row_mask:0xf bank_mask:0x3 bound_ctrl:1
	v_add_f32_dpp v144, v144, v144 row_mirror row_mask:0xf bank_mask:0x3 bound_ctrl:1
	v_add_f32_dpp v136, v147, v147 row_mirror row_mask:0xf bank_mask:0xc bound_ctrl:1
	v_add_f32_dpp v137, v148, v148 row_mirror row_mask:0xf bank_mask:0xc bound_ctrl:1
	v_add_f32_dpp v138, v149, v149 row_mirror row_mask:0xf bank_mask:0xc bound_ctrl:1
	v_add_f32_dpp v139, v150, v150 row_mirror row_mask:0xf bank_mask:0xc bound_ctrl:1
	v_add_f32_dpp v140, v151, v151 row_mirror row_mask:0xf bank_mask:0xc bound_ctrl:1
	v_add_f32_dpp v141, v152, v152 row_mirror row_mask:0xf bank_mask:0xc bound_ctrl:1
	v_add_f32_dpp v142, v153, v153 row_mirror row_mask:0xf bank_mask:0xc bound_ctrl:1
	v_add_f32_dpp v144, v154, v154 row_mirror row_mask:0xf bank_mask:0xc bound_ctrl:1
	v_add_f32_dpp v136, v136, v136 row_half_mirror row_mask:0xf bank_mask:0x5 bound_ctrl:1
	v_add_f32_dpp v137, v137, v137 row_half_mirror row_mask:0xf bank_mask:0x5 bound_ctrl:1
	v_add_f32_dpp v138, v138, v138 row_half_mirror row_mask:0xf bank_mask:0x5 bound_ctrl:1
	v_add_f32_dpp v139, v139, v139 row_half_mirror row_mask:0xf bank_mask:0x5 bound_ctrl:1
	v_add_f32_dpp v136, v140, v140 row_half_mirror row_mask:0xf bank_mask:0xa bound_ctrl:1
	v_add_f32_dpp v137, v141, v141 row_half_mirror row_mask:0xf bank_mask:0xa bound_ctrl:1
	v_add_f32_dpp v138, v142, v142 row_half_mirror row_mask:0xf bank_mask:0xa bound_ctrl:1
	v_add_f32_dpp v139, v144, v144 row_half_mirror row_mask:0xf bank_mask:0xa bound_ctrl:1
	v_add_f32_dpp v136, v136, v136 quad_perm:[2,3,0,1] row_mask:0xf bank_mask:0xf bound_ctrl:1
	v_add_f32_dpp v138, v138, v138 quad_perm:[2,3,0,1] row_mask:0xf bank_mask:0xf bound_ctrl:1
	v_add_f32_dpp v137, v137, v137 quad_perm:[2,3,0,1] row_mask:0xf bank_mask:0xf bound_ctrl:1
	v_add_f32_dpp v139, v139, v139 quad_perm:[2,3,0,1] row_mask:0xf bank_mask:0xf bound_ctrl:1
	v_cndmask_b32_e64 v173, v155, v146, s[28:29]
	v_cndmask_b32_e64 v178, v157, v156, s[28:29]
	v_cndmask_b32_e64 v136, v136, v138, s[24:25]
	v_cndmask_b32_e64 v137, v137, v139, s[24:25]
	v_cndmask_b32_e64 v173, v178, v173, s[24:25]
	v_add_f32_e32 v146, v157, v163
	v_add_f32_dpp v136, v136, v136 quad_perm:[1,0,3,2] row_mask:0xf bank_mask:0xf bound_ctrl:1
	v_add_f32_dpp v137, v137, v137 quad_perm:[1,0,3,2] row_mask:0xf bank_mask:0xf bound_ctrl:1
	v_cndmask_b32_e64 v136, v136, v137, s[28:29]
	v_fmac_f32_e32 v136, 0x3fb8aa3b, v173
	s_nop 1
	v_max_f32_dpp v179, v136, v136 quad_perm:[1,0,3,2] row_mask:0xf bank_mask:0xf bound_ctrl:1
	s_nop 1
	v_max_f32_dpp v180, v179, v179 quad_perm:[2,3,0,1] row_mask:0xf bank_mask:0xf bound_ctrl:1
	v_max_f32_e32 v180, v134, v180
	v_sub_f32_e32 v155, v134, v180
	v_sub_f32_e32 v156, v136, v180
	v_mov_b32_e32 v134, v180
	v_exp_f32_e32 v155, v155
	v_exp_f32_e32 v156, v156
	s_nop 0
	v_mov_b32_dpp v137, v155 row_newbcast:0 row_mask:0xf bank_mask:0xf
	v_mov_b32_dpp v142, v155 row_newbcast:4 row_mask:0xf bank_mask:0xf
	v_mov_b32_dpp v150, v155 row_newbcast:8 row_mask:0xf bank_mask:0xf
	v_mov_b32_dpp v178, v155 row_newbcast:12 row_mask:0xf bank_mask:0xf
	v_add_f32_dpp v157, v156, v156 quad_perm:[1,0,3,2] row_mask:0xf bank_mask:0xf bound_ctrl:1
	v_mov_b32_dpp v138, v156 row_newbcast:0 row_mask:0xf bank_mask:0xf
	v_mov_b32_dpp v139, v156 row_newbcast:1 row_mask:0xf bank_mask:0xf
	v_mov_b32_dpp v140, v156 row_newbcast:2 row_mask:0xf bank_mask:0xf
	v_mov_b32_dpp v141, v156 row_newbcast:3 row_mask:0xf bank_mask:0xf
	v_add_f32_dpp v173, v157, v157 quad_perm:[2,3,0,1] row_mask:0xf bank_mask:0xf bound_ctrl:1
	v_mov_b32_dpp v144, v156 row_newbcast:4 row_mask:0xf bank_mask:0xf
	v_mov_b32_dpp v147, v156 row_newbcast:5 row_mask:0xf bank_mask:0xf
	v_mov_b32_dpp v148, v156 row_newbcast:6 row_mask:0xf bank_mask:0xf
	v_mov_b32_dpp v149, v156 row_newbcast:7 row_mask:0xf bank_mask:0xf
	v_fma_f32 v135, v135, v155, v173
	v_mov_b32_dpp v151, v156 row_newbcast:8 row_mask:0xf bank_mask:0xf
	v_mov_b32_dpp v152, v156 row_newbcast:9 row_mask:0xf bank_mask:0xf
	v_mov_b32_dpp v153, v156 row_newbcast:10 row_mask:0xf bank_mask:0xf
	v_mov_b32_dpp v154, v156 row_newbcast:11 row_mask:0xf bank_mask:0xf
	v_mov_b32_dpp v179, v156 row_newbcast:12 row_mask:0xf bank_mask:0xf
	v_mov_b32_dpp v180, v156 row_newbcast:13 row_mask:0xf bank_mask:0xf
	v_mov_b32_dpp v181, v156 row_newbcast:14 row_mask:0xf bank_mask:0xf
	v_mov_b32_dpp v0, v156 row_newbcast:15 row_mask:0xf bank_mask:0xf
	v_pk_mul_f32 v[118:119], v[118:119], v[136:137] op_sel:[0,1] op_sel_hi:[1,1]
	v_pk_mul_f32 v[120:121], v[120:121], v[136:137] op_sel:[0,1] op_sel_hi:[1,1]
	v_pk_mul_f32 v[122:123], v[122:123], v[142:143] op_sel:[0,0] op_sel_hi:[1,0]
	v_pk_mul_f32 v[124:125], v[124:125], v[142:143] op_sel:[0,0] op_sel_hi:[1,0]
	v_pk_mul_f32 v[126:127], v[126:127], v[150:151] op_sel:[0,0] op_sel_hi:[1,0]
	v_pk_mul_f32 v[128:129], v[128:129], v[150:151] op_sel:[0,0] op_sel_hi:[1,0]
	v_pk_mul_f32 v[130:131], v[130:131], v[178:179] op_sel:[0,0] op_sel_hi:[1,0]
	v_pk_mul_f32 v[132:133], v[132:133], v[178:179] op_sel:[0,0] op_sel_hi:[1,0]
	v_pk_fma_f32 v[118:119], v[138:139], v[66:67], v[118:119] op_sel:[0,0,0] op_sel_hi:[0,1,1]
	v_pk_fma_f32 v[120:121], v[138:139], v[68:69], v[120:121] op_sel:[0,0,0] op_sel_hi:[0,1,1]
	v_pk_fma_f32 v[122:123], v[144:145], v[66:67], v[122:123] op_sel:[0,0,0] op_sel_hi:[0,1,1]
	v_pk_fma_f32 v[124:125], v[144:145], v[68:69], v[124:125] op_sel:[0,0,0] op_sel_hi:[0,1,1]
	v_pk_fma_f32 v[126:127], v[150:151], v[66:67], v[126:127] op_sel:[1,0,0] op_sel_hi:[1,1,1]
	v_pk_fma_f32 v[128:129], v[150:151], v[68:69], v[128:129] op_sel:[1,0,0] op_sel_hi:[1,1,1]
	v_pk_fma_f32 v[130:131], v[178:179], v[66:67], v[130:131] op_sel:[1,0,0] op_sel_hi:[1,1,1]
	v_pk_fma_f32 v[132:133], v[178:179], v[68:69], v[132:133] op_sel:[1,0,0] op_sel_hi:[1,1,1]
	v_pk_fma_f32 v[118:119], v[138:139], v[70:71], v[118:119] op_sel:[1,0,0] op_sel_hi:[1,1,1]
	v_pk_fma_f32 v[120:121], v[138:139], v[72:73], v[120:121] op_sel:[1,0,0] op_sel_hi:[1,1,1]
	v_pk_fma_f32 v[122:123], v[146:147], v[70:71], v[122:123] op_sel:[1,0,0] op_sel_hi:[1,1,1]
	v_pk_fma_f32 v[124:125], v[146:147], v[72:73], v[124:125] op_sel:[1,0,0] op_sel_hi:[1,1,1]
	v_pk_fma_f32 v[126:127], v[152:153], v[70:71], v[126:127] op_sel:[0,0,0] op_sel_hi:[0,1,1]
	v_pk_fma_f32 v[128:129], v[152:153], v[72:73], v[128:129] op_sel:[0,0,0] op_sel_hi:[0,1,1]
	v_pk_fma_f32 v[130:131], v[180:181], v[70:71], v[130:131] op_sel:[0,0,0] op_sel_hi:[0,1,1]
	v_pk_fma_f32 v[132:133], v[180:181], v[72:73], v[132:133] op_sel:[0,0,0] op_sel_hi:[0,1,1]
	v_pk_fma_f32 v[118:119], v[140:141], v[74:75], v[118:119] op_sel:[0,0,0] op_sel_hi:[0,1,1]
	v_pk_fma_f32 v[120:121], v[140:141], v[76:77], v[120:121] op_sel:[0,0,0] op_sel_hi:[0,1,1]
	v_pk_fma_f32 v[122:123], v[148:149], v[74:75], v[122:123] op_sel:[0,0,0] op_sel_hi:[0,1,1]
	v_pk_fma_f32 v[124:125], v[148:149], v[76:77], v[124:125] op_sel:[0,0,0] op_sel_hi:[0,1,1]
	v_pk_fma_f32 v[126:127], v[152:153], v[74:75], v[126:127] op_sel:[1,0,0] op_sel_hi:[1,1,1]
	v_pk_fma_f32 v[128:129], v[152:153], v[76:77], v[128:129] op_sel:[1,0,0] op_sel_hi:[1,1,1]
	v_pk_fma_f32 v[130:131], v[180:181], v[74:75], v[130:131] op_sel:[1,0,0] op_sel_hi:[1,1,1]
	v_pk_fma_f32 v[132:133], v[180:181], v[76:77], v[132:133] op_sel:[1,0,0] op_sel_hi:[1,1,1]
	v_pk_fma_f32 v[118:119], v[140:141], v[78:79], v[118:119] op_sel:[1,0,0] op_sel_hi:[1,1,1]
	v_pk_fma_f32 v[120:121], v[140:141], v[80:81], v[120:121] op_sel:[1,0,0] op_sel_hi:[1,1,1]
	v_pk_fma_f32 v[122:123], v[148:149], v[78:79], v[122:123] op_sel:[1,0,0] op_sel_hi:[1,1,1]
	v_pk_fma_f32 v[124:125], v[148:149], v[80:81], v[124:125] op_sel:[1,0,0] op_sel_hi:[1,1,1]
	v_pk_fma_f32 v[126:127], v[154:155], v[78:79], v[126:127] op_sel:[0,0,0] op_sel_hi:[0,1,1]
	v_pk_fma_f32 v[128:129], v[154:155], v[80:81], v[128:129] op_sel:[0,0,0] op_sel_hi:[0,1,1]
	v_pk_fma_f32 v[130:131], v[0:1], v[78:79], v[130:131] op_sel:[0,0,0] op_sel_hi:[0,1,1]
	v_pk_fma_f32 v[132:133], v[0:1], v[80:81], v[132:133] op_sel:[0,0,0] op_sel_hi:[0,1,1]
	s_waitcnt vmcnt(12)
	v_pk_mul_f32 v[98:99], v[116:117], v[52:53]
	v_pk_mul_f32 v[100:101], v[116:117], v[60:61]
	v_pk_mul_f32 v[174:175], v[116:117], v[56:57]
	v_pk_mul_f32 v[176:177], v[116:117], v[64:65]
	v_pk_fma_f32 v[98:99], v[114:115], v[50:51], v[98:99]
	v_pk_fma_f32 v[100:101], v[114:115], v[58:59], v[100:101]
	v_pk_fma_f32 v[174:175], v[114:115], v[54:55], v[174:175]
	v_pk_fma_f32 v[176:177], v[114:115], v[62:63], v[176:177]
	v_add_f32_e32 v136, v98, v99
	v_add_f32_e32 v137, v100, v101
	v_add_f32_e32 v138, v174, v175
	v_add_f32_e32 v139, v176, v177
	v_pk_mul_f32 v[98:99], v[112:113], v[52:53]
	v_pk_mul_f32 v[100:101], v[112:113], v[60:61]
	v_pk_mul_f32 v[174:175], v[112:113], v[56:57]
	v_pk_mul_f32 v[176:177], v[112:113], v[64:65]
	v_pk_fma_f32 v[98:99], v[110:111], v[50:51], v[98:99]
	v_pk_fma_f32 v[100:101], v[110:111], v[58:59], v[100:101]
	v_pk_fma_f32 v[174:175], v[110:111], v[54:55], v[174:175]
	v_pk_fma_f32 v[176:177], v[110:111], v[62:63], v[176:177]
	v_add_f32_e32 v140, v98, v99
	v_add_f32_e32 v141, v100, v101
	v_add_f32_e32 v142, v174, v175
	v_add_f32_e32 v144, v176, v177
	v_pk_mul_f32 v[98:99], v[108:109], v[52:53]
	v_pk_mul_f32 v[100:101], v[108:109], v[60:61]
	v_pk_mul_f32 v[174:175], v[108:109], v[56:57]
	v_pk_mul_f32 v[176:177], v[108:109], v[64:65]
	v_pk_fma_f32 v[98:99], v[106:107], v[50:51], v[98:99]
	v_pk_fma_f32 v[100:101], v[106:107], v[58:59], v[100:101]
	v_pk_fma_f32 v[174:175], v[106:107], v[54:55], v[174:175]
	v_pk_fma_f32 v[176:177], v[106:107], v[62:63], v[176:177]
	v_add_f32_e32 v147, v98, v99
	v_add_f32_e32 v148, v100, v101
	v_add_f32_e32 v149, v174, v175
	v_add_f32_e32 v150, v176, v177
	v_pk_mul_f32 v[98:99], v[104:105], v[52:53]
	v_pk_mul_f32 v[100:101], v[104:105], v[60:61]
	v_pk_mul_f32 v[174:175], v[104:105], v[56:57]
	v_pk_mul_f32 v[176:177], v[104:105], v[64:65]
	v_pk_fma_f32 v[98:99], v[102:103], v[50:51], v[98:99]
	v_pk_fma_f32 v[100:101], v[102:103], v[58:59], v[100:101]
	v_pk_fma_f32 v[174:175], v[102:103], v[54:55], v[174:175]
	v_pk_fma_f32 v[176:177], v[102:103], v[62:63], v[176:177]
	v_add_f32_e32 v151, v98, v99
	v_add_f32_e32 v152, v100, v101
	v_add_f32_e32 v153, v174, v175
	v_add_f32_e32 v154, v176, v177
	v_add_f32_e32 v155, v146, v171
	v_add_f32_e32 v156, v155, v170
	v_add_f32_e32 v157, v156, v169
	v_add_f32_dpp v136, v136, v136 row_mirror row_mask:0xf bank_mask:0x3 bound_ctrl:1
	v_add_f32_dpp v137, v137, v137 row_mirror row_mask:0xf bank_mask:0x3 bound_ctrl:1
	v_add_f32_dpp v138, v138, v138 row_mirror row_mask:0xf bank_mask:0x3 bound_ctrl:1
	v_add_f32_dpp v139, v139, v139 row_mirror row_mask:0xf bank_mask:0x3 bound_ctrl:1
	v_add_f32_dpp v140, v140, v140 row_mirror row_mask:0xf bank_mask:0x3 bound_ctrl:1
	v_add_f32_dpp v141, v141, v141 row_mirror row_mask:0xf bank_mask:0x3 bound_ctrl:1
	v_add_f32_dpp v142, v142, v142 row_mirror row_mask:0xf bank_mask:0x3 bound_ctrl:1
	v_add_f32_dpp v144, v144, v144 row_mirror row_mask:0xf bank_mask:0x3 bound_ctrl:1
	v_add_f32_dpp v136, v147, v147 row_mirror row_mask:0xf bank_mask:0xc bound_ctrl:1
	v_add_f32_dpp v137, v148, v148 row_mirror row_mask:0xf bank_mask:0xc bound_ctrl:1
	v_add_f32_dpp v138, v149, v149 row_mirror row_mask:0xf bank_mask:0xc bound_ctrl:1
	v_add_f32_dpp v139, v150, v150 row_mirror row_mask:0xf bank_mask:0xc bound_ctrl:1
	v_add_f32_dpp v140, v151, v151 row_mirror row_mask:0xf bank_mask:0xc bound_ctrl:1
	v_add_f32_dpp v141, v152, v152 row_mirror row_mask:0xf bank_mask:0xc bound_ctrl:1
	v_add_f32_dpp v142, v153, v153 row_mirror row_mask:0xf bank_mask:0xc bound_ctrl:1
	v_add_f32_dpp v144, v154, v154 row_mirror row_mask:0xf bank_mask:0xc bound_ctrl:1
	v_add_f32_dpp v136, v136, v136 row_half_mirror row_mask:0xf bank_mask:0x5 bound_ctrl:1
	v_add_f32_dpp v137, v137, v137 row_half_mirror row_mask:0xf bank_mask:0x5 bound_ctrl:1
	v_add_f32_dpp v138, v138, v138 row_half_mirror row_mask:0xf bank_mask:0x5 bound_ctrl:1
	v_add_f32_dpp v139, v139, v139 row_half_mirror row_mask:0xf bank_mask:0x5 bound_ctrl:1
	v_add_f32_dpp v136, v140, v140 row_half_mirror row_mask:0xf bank_mask:0xa bound_ctrl:1
	v_add_f32_dpp v137, v141, v141 row_half_mirror row_mask:0xf bank_mask:0xa bound_ctrl:1
	v_add_f32_dpp v138, v142, v142 row_half_mirror row_mask:0xf bank_mask:0xa bound_ctrl:1
	v_add_f32_dpp v139, v144, v144 row_half_mirror row_mask:0xf bank_mask:0xa bound_ctrl:1
	v_add_f32_dpp v136, v136, v136 quad_perm:[2,3,0,1] row_mask:0xf bank_mask:0xf bound_ctrl:1
	v_add_f32_dpp v138, v138, v138 quad_perm:[2,3,0,1] row_mask:0xf bank_mask:0xf bound_ctrl:1
	v_add_f32_dpp v137, v137, v137 quad_perm:[2,3,0,1] row_mask:0xf bank_mask:0xf bound_ctrl:1
	v_add_f32_dpp v139, v139, v139 quad_perm:[2,3,0,1] row_mask:0xf bank_mask:0xf bound_ctrl:1
	v_cndmask_b32_e64 v173, v155, v146, s[28:29]
	v_cndmask_b32_e64 v178, v157, v156, s[28:29]
	v_cndmask_b32_e64 v136, v136, v138, s[24:25]
	v_cndmask_b32_e64 v137, v137, v139, s[24:25]
	v_cndmask_b32_e64 v173, v178, v173, s[24:25]
	v_add_f32_e32 v146, v157, v167
	v_add_f32_dpp v136, v136, v136 quad_perm:[1,0,3,2] row_mask:0xf bank_mask:0xf bound_ctrl:1
	v_add_f32_dpp v137, v137, v137 quad_perm:[1,0,3,2] row_mask:0xf bank_mask:0xf bound_ctrl:1
	v_cndmask_b32_e64 v136, v136, v137, s[28:29]
	v_fmac_f32_e32 v136, 0x3fb8aa3b, v173
	s_nop 1
	v_max_f32_dpp v179, v136, v136 quad_perm:[1,0,3,2] row_mask:0xf bank_mask:0xf bound_ctrl:1
	s_nop 1
	v_max_f32_dpp v180, v179, v179 quad_perm:[2,3,0,1] row_mask:0xf bank_mask:0xf bound_ctrl:1
	v_max_f32_e32 v180, v134, v180
	v_sub_f32_e32 v155, v134, v180
	v_sub_f32_e32 v156, v136, v180
	v_mov_b32_e32 v134, v180
	v_exp_f32_e32 v155, v155
	v_exp_f32_e32 v156, v156
	s_nop 0
	v_mov_b32_dpp v137, v155 row_newbcast:0 row_mask:0xf bank_mask:0xf
	v_mov_b32_dpp v142, v155 row_newbcast:4 row_mask:0xf bank_mask:0xf
	v_mov_b32_dpp v150, v155 row_newbcast:8 row_mask:0xf bank_mask:0xf
	v_mov_b32_dpp v178, v155 row_newbcast:12 row_mask:0xf bank_mask:0xf
	v_add_f32_dpp v157, v156, v156 quad_perm:[1,0,3,2] row_mask:0xf bank_mask:0xf bound_ctrl:1
	v_mov_b32_dpp v138, v156 row_newbcast:0 row_mask:0xf bank_mask:0xf
	v_mov_b32_dpp v139, v156 row_newbcast:1 row_mask:0xf bank_mask:0xf
	v_mov_b32_dpp v140, v156 row_newbcast:2 row_mask:0xf bank_mask:0xf
	v_mov_b32_dpp v141, v156 row_newbcast:3 row_mask:0xf bank_mask:0xf
	v_add_f32_dpp v173, v157, v157 quad_perm:[2,3,0,1] row_mask:0xf bank_mask:0xf bound_ctrl:1
	v_mov_b32_dpp v144, v156 row_newbcast:4 row_mask:0xf bank_mask:0xf
	v_mov_b32_dpp v147, v156 row_newbcast:5 row_mask:0xf bank_mask:0xf
	v_mov_b32_dpp v148, v156 row_newbcast:6 row_mask:0xf bank_mask:0xf
	v_mov_b32_dpp v149, v156 row_newbcast:7 row_mask:0xf bank_mask:0xf
	v_fma_f32 v135, v135, v155, v173
	v_mov_b32_dpp v151, v156 row_newbcast:8 row_mask:0xf bank_mask:0xf
	v_mov_b32_dpp v152, v156 row_newbcast:9 row_mask:0xf bank_mask:0xf
	v_mov_b32_dpp v153, v156 row_newbcast:10 row_mask:0xf bank_mask:0xf
	v_mov_b32_dpp v154, v156 row_newbcast:11 row_mask:0xf bank_mask:0xf
	v_mov_b32_dpp v179, v156 row_newbcast:12 row_mask:0xf bank_mask:0xf
	v_mov_b32_dpp v180, v156 row_newbcast:13 row_mask:0xf bank_mask:0xf
	v_mov_b32_dpp v181, v156 row_newbcast:14 row_mask:0xf bank_mask:0xf
	v_mov_b32_dpp v0, v156 row_newbcast:15 row_mask:0xf bank_mask:0xf
	v_pk_mul_f32 v[118:119], v[118:119], v[136:137] op_sel:[0,1] op_sel_hi:[1,1]
	v_pk_mul_f32 v[120:121], v[120:121], v[136:137] op_sel:[0,1] op_sel_hi:[1,1]
	v_pk_mul_f32 v[122:123], v[122:123], v[142:143] op_sel:[0,0] op_sel_hi:[1,0]
	v_pk_mul_f32 v[124:125], v[124:125], v[142:143] op_sel:[0,0] op_sel_hi:[1,0]
	v_pk_mul_f32 v[126:127], v[126:127], v[150:151] op_sel:[0,0] op_sel_hi:[1,0]
	v_pk_mul_f32 v[128:129], v[128:129], v[150:151] op_sel:[0,0] op_sel_hi:[1,0]
	v_pk_mul_f32 v[130:131], v[130:131], v[178:179] op_sel:[0,0] op_sel_hi:[1,0]
	v_pk_mul_f32 v[132:133], v[132:133], v[178:179] op_sel:[0,0] op_sel_hi:[1,0]
	v_pk_fma_f32 v[118:119], v[138:139], v[22:23], v[118:119] op_sel:[0,0,0] op_sel_hi:[0,1,1]
	v_pk_fma_f32 v[120:121], v[138:139], v[24:25], v[120:121] op_sel:[0,0,0] op_sel_hi:[0,1,1]
	v_pk_fma_f32 v[122:123], v[144:145], v[22:23], v[122:123] op_sel:[0,0,0] op_sel_hi:[0,1,1]
	v_pk_fma_f32 v[124:125], v[144:145], v[24:25], v[124:125] op_sel:[0,0,0] op_sel_hi:[0,1,1]
	v_pk_fma_f32 v[126:127], v[150:151], v[22:23], v[126:127] op_sel:[1,0,0] op_sel_hi:[1,1,1]
	v_pk_fma_f32 v[128:129], v[150:151], v[24:25], v[128:129] op_sel:[1,0,0] op_sel_hi:[1,1,1]
	v_pk_fma_f32 v[130:131], v[178:179], v[22:23], v[130:131] op_sel:[1,0,0] op_sel_hi:[1,1,1]
	v_pk_fma_f32 v[132:133], v[178:179], v[24:25], v[132:133] op_sel:[1,0,0] op_sel_hi:[1,1,1]
	v_pk_fma_f32 v[118:119], v[138:139], v[18:19], v[118:119] op_sel:[1,0,0] op_sel_hi:[1,1,1]
	v_pk_fma_f32 v[120:121], v[138:139], v[20:21], v[120:121] op_sel:[1,0,0] op_sel_hi:[1,1,1]
	v_pk_fma_f32 v[122:123], v[146:147], v[18:19], v[122:123] op_sel:[1,0,0] op_sel_hi:[1,1,1]
	v_pk_fma_f32 v[124:125], v[146:147], v[20:21], v[124:125] op_sel:[1,0,0] op_sel_hi:[1,1,1]
	v_pk_fma_f32 v[126:127], v[152:153], v[18:19], v[126:127] op_sel:[0,0,0] op_sel_hi:[0,1,1]
	v_pk_fma_f32 v[128:129], v[152:153], v[20:21], v[128:129] op_sel:[0,0,0] op_sel_hi:[0,1,1]
	v_pk_fma_f32 v[130:131], v[180:181], v[18:19], v[130:131] op_sel:[0,0,0] op_sel_hi:[0,1,1]
	v_pk_fma_f32 v[132:133], v[180:181], v[20:21], v[132:133] op_sel:[0,0,0] op_sel_hi:[0,1,1]
	v_pk_fma_f32 v[118:119], v[140:141], v[26:27], v[118:119] op_sel:[0,0,0] op_sel_hi:[0,1,1]
	v_pk_fma_f32 v[120:121], v[140:141], v[28:29], v[120:121] op_sel:[0,0,0] op_sel_hi:[0,1,1]
	v_pk_fma_f32 v[122:123], v[148:149], v[26:27], v[122:123] op_sel:[0,0,0] op_sel_hi:[0,1,1]
	v_pk_fma_f32 v[124:125], v[148:149], v[28:29], v[124:125] op_sel:[0,0,0] op_sel_hi:[0,1,1]
	v_pk_fma_f32 v[126:127], v[152:153], v[26:27], v[126:127] op_sel:[1,0,0] op_sel_hi:[1,1,1]
	v_pk_fma_f32 v[128:129], v[152:153], v[28:29], v[128:129] op_sel:[1,0,0] op_sel_hi:[1,1,1]
	v_pk_fma_f32 v[130:131], v[180:181], v[26:27], v[130:131] op_sel:[1,0,0] op_sel_hi:[1,1,1]
	v_pk_fma_f32 v[132:133], v[180:181], v[28:29], v[132:133] op_sel:[1,0,0] op_sel_hi:[1,1,1]
	v_pk_fma_f32 v[118:119], v[140:141], v[30:31], v[118:119] op_sel:[1,0,0] op_sel_hi:[1,1,1]
	v_pk_fma_f32 v[120:121], v[140:141], v[32:33], v[120:121] op_sel:[1,0,0] op_sel_hi:[1,1,1]
	v_pk_fma_f32 v[122:123], v[148:149], v[30:31], v[122:123] op_sel:[1,0,0] op_sel_hi:[1,1,1]
	v_pk_fma_f32 v[124:125], v[148:149], v[32:33], v[124:125] op_sel:[1,0,0] op_sel_hi:[1,1,1]
	v_pk_fma_f32 v[126:127], v[154:155], v[30:31], v[126:127] op_sel:[0,0,0] op_sel_hi:[0,1,1]
	v_pk_fma_f32 v[128:129], v[154:155], v[32:33], v[128:129] op_sel:[0,0,0] op_sel_hi:[0,1,1]
	v_pk_fma_f32 v[130:131], v[0:1], v[30:31], v[130:131] op_sel:[0,0,0] op_sel_hi:[0,1,1]
	v_pk_fma_f32 v[132:133], v[0:1], v[32:33], v[132:133] op_sel:[0,0,0] op_sel_hi:[0,1,1]
	s_waitcnt vmcnt(0)
	v_pk_mul_f32 v[98:99], v[116:117], v[36:37]
	v_pk_mul_f32 v[100:101], v[116:117], v[44:45]
	v_pk_mul_f32 v[174:175], v[116:117], v[40:41]
	v_pk_mul_f32 v[176:177], v[116:117], v[48:49]
	v_pk_fma_f32 v[98:99], v[114:115], v[34:35], v[98:99]
	v_pk_fma_f32 v[100:101], v[114:115], v[42:43], v[100:101]
	v_pk_fma_f32 v[174:175], v[114:115], v[38:39], v[174:175]
	v_pk_fma_f32 v[176:177], v[114:115], v[46:47], v[176:177]
	v_add_f32_e32 v136, v98, v99
	v_add_f32_e32 v137, v100, v101
	v_add_f32_e32 v138, v174, v175
	v_add_f32_e32 v139, v176, v177
	v_pk_mul_f32 v[98:99], v[112:113], v[36:37]
	v_pk_mul_f32 v[100:101], v[112:113], v[44:45]
	v_pk_mul_f32 v[174:175], v[112:113], v[40:41]
	v_pk_mul_f32 v[176:177], v[112:113], v[48:49]
	v_pk_fma_f32 v[98:99], v[110:111], v[34:35], v[98:99]
	v_pk_fma_f32 v[100:101], v[110:111], v[42:43], v[100:101]
	v_pk_fma_f32 v[174:175], v[110:111], v[38:39], v[174:175]
	v_pk_fma_f32 v[176:177], v[110:111], v[46:47], v[176:177]
	v_add_f32_e32 v140, v98, v99
	v_add_f32_e32 v141, v100, v101
	v_add_f32_e32 v142, v174, v175
	v_add_f32_e32 v144, v176, v177
	v_pk_mul_f32 v[98:99], v[108:109], v[36:37]
	v_pk_mul_f32 v[100:101], v[108:109], v[44:45]
	v_pk_mul_f32 v[174:175], v[108:109], v[40:41]
	v_pk_mul_f32 v[176:177], v[108:109], v[48:49]
	v_pk_fma_f32 v[98:99], v[106:107], v[34:35], v[98:99]
	v_pk_fma_f32 v[100:101], v[106:107], v[42:43], v[100:101]
	v_pk_fma_f32 v[174:175], v[106:107], v[38:39], v[174:175]
	v_pk_fma_f32 v[176:177], v[106:107], v[46:47], v[176:177]
	v_add_f32_e32 v147, v98, v99
	v_add_f32_e32 v148, v100, v101
	v_add_f32_e32 v149, v174, v175
	v_add_f32_e32 v150, v176, v177
	v_pk_mul_f32 v[98:99], v[104:105], v[36:37]
	v_pk_mul_f32 v[100:101], v[104:105], v[44:45]
	v_pk_mul_f32 v[174:175], v[104:105], v[40:41]
	v_pk_mul_f32 v[176:177], v[104:105], v[48:49]
	v_pk_fma_f32 v[98:99], v[102:103], v[34:35], v[98:99]
	v_pk_fma_f32 v[100:101], v[102:103], v[42:43], v[100:101]
	v_pk_fma_f32 v[174:175], v[102:103], v[38:39], v[174:175]
	v_pk_fma_f32 v[176:177], v[102:103], v[46:47], v[176:177]
	v_add_f32_e32 v151, v98, v99
	v_add_f32_e32 v152, v100, v101
	v_add_f32_e32 v153, v174, v175
	v_add_f32_e32 v154, v176, v177
	v_add_f32_e32 v155, v146, v166
	v_add_f32_e32 v156, v155, v165
	v_add_f32_e32 v157, v156, v164
	v_add_f32_dpp v136, v136, v136 row_mirror row_mask:0xf bank_mask:0x3 bound_ctrl:1
	v_add_f32_dpp v137, v137, v137 row_mirror row_mask:0xf bank_mask:0x3 bound_ctrl:1
	v_add_f32_dpp v138, v138, v138 row_mirror row_mask:0xf bank_mask:0x3 bound_ctrl:1
	v_add_f32_dpp v139, v139, v139 row_mirror row_mask:0xf bank_mask:0x3 bound_ctrl:1
	v_add_f32_dpp v140, v140, v140 row_mirror row_mask:0xf bank_mask:0x3 bound_ctrl:1
	v_add_f32_dpp v141, v141, v141 row_mirror row_mask:0xf bank_mask:0x3 bound_ctrl:1
	v_add_f32_dpp v142, v142, v142 row_mirror row_mask:0xf bank_mask:0x3 bound_ctrl:1
	v_add_f32_dpp v144, v144, v144 row_mirror row_mask:0xf bank_mask:0x3 bound_ctrl:1
	v_add_f32_dpp v136, v147, v147 row_mirror row_mask:0xf bank_mask:0xc bound_ctrl:1
	v_add_f32_dpp v137, v148, v148 row_mirror row_mask:0xf bank_mask:0xc bound_ctrl:1
	v_add_f32_dpp v138, v149, v149 row_mirror row_mask:0xf bank_mask:0xc bound_ctrl:1
	v_add_f32_dpp v139, v150, v150 row_mirror row_mask:0xf bank_mask:0xc bound_ctrl:1
	v_add_f32_dpp v140, v151, v151 row_mirror row_mask:0xf bank_mask:0xc bound_ctrl:1
	v_add_f32_dpp v141, v152, v152 row_mirror row_mask:0xf bank_mask:0xc bound_ctrl:1
	v_add_f32_dpp v142, v153, v153 row_mirror row_mask:0xf bank_mask:0xc bound_ctrl:1
	v_add_f32_dpp v144, v154, v154 row_mirror row_mask:0xf bank_mask:0xc bound_ctrl:1
	v_add_f32_dpp v136, v136, v136 row_half_mirror row_mask:0xf bank_mask:0x5 bound_ctrl:1
	v_add_f32_dpp v137, v137, v137 row_half_mirror row_mask:0xf bank_mask:0x5 bound_ctrl:1
	v_add_f32_dpp v138, v138, v138 row_half_mirror row_mask:0xf bank_mask:0x5 bound_ctrl:1
	v_add_f32_dpp v139, v139, v139 row_half_mirror row_mask:0xf bank_mask:0x5 bound_ctrl:1
	v_add_f32_dpp v136, v140, v140 row_half_mirror row_mask:0xf bank_mask:0xa bound_ctrl:1
	v_add_f32_dpp v137, v141, v141 row_half_mirror row_mask:0xf bank_mask:0xa bound_ctrl:1
	v_add_f32_dpp v138, v142, v142 row_half_mirror row_mask:0xf bank_mask:0xa bound_ctrl:1
	v_add_f32_dpp v139, v144, v144 row_half_mirror row_mask:0xf bank_mask:0xa bound_ctrl:1
	v_add_f32_dpp v136, v136, v136 quad_perm:[2,3,0,1] row_mask:0xf bank_mask:0xf bound_ctrl:1
	v_add_f32_dpp v138, v138, v138 quad_perm:[2,3,0,1] row_mask:0xf bank_mask:0xf bound_ctrl:1
	v_add_f32_dpp v137, v137, v137 quad_perm:[2,3,0,1] row_mask:0xf bank_mask:0xf bound_ctrl:1
	v_add_f32_dpp v139, v139, v139 quad_perm:[2,3,0,1] row_mask:0xf bank_mask:0xf bound_ctrl:1
	v_cndmask_b32_e64 v173, v155, v146, s[28:29]
	v_cndmask_b32_e64 v178, v157, v156, s[28:29]
	v_cndmask_b32_e64 v136, v136, v138, s[24:25]
	v_cndmask_b32_e64 v137, v137, v139, s[24:25]
	v_cndmask_b32_e64 v173, v178, v173, s[24:25]
	v_add_f32_e32 v146, v157, v168
	v_add_f32_dpp v136, v136, v136 quad_perm:[1,0,3,2] row_mask:0xf bank_mask:0xf bound_ctrl:1
	v_add_f32_dpp v137, v137, v137 quad_perm:[1,0,3,2] row_mask:0xf bank_mask:0xf bound_ctrl:1
	v_cndmask_b32_e64 v136, v136, v137, s[28:29]
	v_fmac_f32_e32 v136, 0x3fb8aa3b, v173
	s_nop 1
	v_max_f32_dpp v179, v136, v136 quad_perm:[1,0,3,2] row_mask:0xf bank_mask:0xf bound_ctrl:1
	s_nop 1
	v_max_f32_dpp v180, v179, v179 quad_perm:[2,3,0,1] row_mask:0xf bank_mask:0xf bound_ctrl:1
	v_max_f32_e32 v180, v134, v180
	v_sub_f32_e32 v155, v134, v180
	v_sub_f32_e32 v156, v136, v180
	v_mov_b32_e32 v134, v180
	v_exp_f32_e32 v155, v155
	v_exp_f32_e32 v156, v156
	s_nop 0
	v_mov_b32_dpp v137, v155 row_newbcast:0 row_mask:0xf bank_mask:0xf
	v_mov_b32_dpp v142, v155 row_newbcast:4 row_mask:0xf bank_mask:0xf
	v_mov_b32_dpp v150, v155 row_newbcast:8 row_mask:0xf bank_mask:0xf
	v_mov_b32_dpp v178, v155 row_newbcast:12 row_mask:0xf bank_mask:0xf
	v_add_f32_dpp v157, v156, v156 quad_perm:[1,0,3,2] row_mask:0xf bank_mask:0xf bound_ctrl:1
	v_mov_b32_dpp v138, v156 row_newbcast:0 row_mask:0xf bank_mask:0xf
	v_mov_b32_dpp v139, v156 row_newbcast:1 row_mask:0xf bank_mask:0xf
	v_mov_b32_dpp v140, v156 row_newbcast:2 row_mask:0xf bank_mask:0xf
	v_mov_b32_dpp v141, v156 row_newbcast:3 row_mask:0xf bank_mask:0xf
	v_add_f32_dpp v173, v157, v157 quad_perm:[2,3,0,1] row_mask:0xf bank_mask:0xf bound_ctrl:1
	v_mov_b32_dpp v144, v156 row_newbcast:4 row_mask:0xf bank_mask:0xf
	v_mov_b32_dpp v147, v156 row_newbcast:5 row_mask:0xf bank_mask:0xf
	v_mov_b32_dpp v148, v156 row_newbcast:6 row_mask:0xf bank_mask:0xf
	v_mov_b32_dpp v149, v156 row_newbcast:7 row_mask:0xf bank_mask:0xf
	v_fma_f32 v135, v135, v155, v173
	v_mov_b32_dpp v151, v156 row_newbcast:8 row_mask:0xf bank_mask:0xf
	v_mov_b32_dpp v152, v156 row_newbcast:9 row_mask:0xf bank_mask:0xf
	v_mov_b32_dpp v153, v156 row_newbcast:10 row_mask:0xf bank_mask:0xf
	v_mov_b32_dpp v154, v156 row_newbcast:11 row_mask:0xf bank_mask:0xf
	v_mov_b32_dpp v179, v156 row_newbcast:12 row_mask:0xf bank_mask:0xf
	v_mov_b32_dpp v180, v156 row_newbcast:13 row_mask:0xf bank_mask:0xf
	v_mov_b32_dpp v181, v156 row_newbcast:14 row_mask:0xf bank_mask:0xf
	v_mov_b32_dpp v0, v156 row_newbcast:15 row_mask:0xf bank_mask:0xf
	v_pk_mul_f32 v[118:119], v[118:119], v[136:137] op_sel:[0,1] op_sel_hi:[1,1]
	v_pk_mul_f32 v[120:121], v[120:121], v[136:137] op_sel:[0,1] op_sel_hi:[1,1]
	v_pk_mul_f32 v[122:123], v[122:123], v[142:143] op_sel:[0,0] op_sel_hi:[1,0]
	v_pk_mul_f32 v[124:125], v[124:125], v[142:143] op_sel:[0,0] op_sel_hi:[1,0]
	v_pk_mul_f32 v[126:127], v[126:127], v[150:151] op_sel:[0,0] op_sel_hi:[1,0]
	v_pk_mul_f32 v[128:129], v[128:129], v[150:151] op_sel:[0,0] op_sel_hi:[1,0]
	v_pk_mul_f32 v[130:131], v[130:131], v[178:179] op_sel:[0,0] op_sel_hi:[1,0]
	v_pk_mul_f32 v[132:133], v[132:133], v[178:179] op_sel:[0,0] op_sel_hi:[1,0]
	v_pk_fma_f32 v[118:119], v[138:139], v[2:3], v[118:119] op_sel:[0,0,0] op_sel_hi:[0,1,1]
	v_pk_fma_f32 v[120:121], v[138:139], v[4:5], v[120:121] op_sel:[0,0,0] op_sel_hi:[0,1,1]
	v_pk_fma_f32 v[122:123], v[144:145], v[2:3], v[122:123] op_sel:[0,0,0] op_sel_hi:[0,1,1]
	v_pk_fma_f32 v[124:125], v[144:145], v[4:5], v[124:125] op_sel:[0,0,0] op_sel_hi:[0,1,1]
	v_pk_fma_f32 v[126:127], v[150:151], v[2:3], v[126:127] op_sel:[1,0,0] op_sel_hi:[1,1,1]
	v_pk_fma_f32 v[128:129], v[150:151], v[4:5], v[128:129] op_sel:[1,0,0] op_sel_hi:[1,1,1]
	v_pk_fma_f32 v[130:131], v[178:179], v[2:3], v[130:131] op_sel:[1,0,0] op_sel_hi:[1,1,1]
	v_pk_fma_f32 v[132:133], v[178:179], v[4:5], v[132:133] op_sel:[1,0,0] op_sel_hi:[1,1,1]
	v_pk_fma_f32 v[118:119], v[138:139], v[6:7], v[118:119] op_sel:[1,0,0] op_sel_hi:[1,1,1]
	v_pk_fma_f32 v[120:121], v[138:139], v[8:9], v[120:121] op_sel:[1,0,0] op_sel_hi:[1,1,1]
	v_pk_fma_f32 v[122:123], v[146:147], v[6:7], v[122:123] op_sel:[1,0,0] op_sel_hi:[1,1,1]
	v_pk_fma_f32 v[124:125], v[146:147], v[8:9], v[124:125] op_sel:[1,0,0] op_sel_hi:[1,1,1]
	v_pk_fma_f32 v[126:127], v[152:153], v[6:7], v[126:127] op_sel:[0,0,0] op_sel_hi:[0,1,1]
	v_pk_fma_f32 v[128:129], v[152:153], v[8:9], v[128:129] op_sel:[0,0,0] op_sel_hi:[0,1,1]
	v_pk_fma_f32 v[130:131], v[180:181], v[6:7], v[130:131] op_sel:[0,0,0] op_sel_hi:[0,1,1]
	v_pk_fma_f32 v[132:133], v[180:181], v[8:9], v[132:133] op_sel:[0,0,0] op_sel_hi:[0,1,1]
	v_pk_fma_f32 v[118:119], v[140:141], v[10:11], v[118:119] op_sel:[0,0,0] op_sel_hi:[0,1,1]
	v_pk_fma_f32 v[120:121], v[140:141], v[12:13], v[120:121] op_sel:[0,0,0] op_sel_hi:[0,1,1]
	v_pk_fma_f32 v[122:123], v[148:149], v[10:11], v[122:123] op_sel:[0,0,0] op_sel_hi:[0,1,1]
	v_pk_fma_f32 v[124:125], v[148:149], v[12:13], v[124:125] op_sel:[0,0,0] op_sel_hi:[0,1,1]
	v_pk_fma_f32 v[126:127], v[152:153], v[10:11], v[126:127] op_sel:[1,0,0] op_sel_hi:[1,1,1]
	v_pk_fma_f32 v[128:129], v[152:153], v[12:13], v[128:129] op_sel:[1,0,0] op_sel_hi:[1,1,1]
	v_pk_fma_f32 v[130:131], v[180:181], v[10:11], v[130:131] op_sel:[1,0,0] op_sel_hi:[1,1,1]
	v_pk_fma_f32 v[132:133], v[180:181], v[12:13], v[132:133] op_sel:[1,0,0] op_sel_hi:[1,1,1]
	v_pk_fma_f32 v[118:119], v[140:141], v[14:15], v[118:119] op_sel:[1,0,0] op_sel_hi:[1,1,1]
	v_pk_fma_f32 v[120:121], v[140:141], v[16:17], v[120:121] op_sel:[1,0,0] op_sel_hi:[1,1,1]
	v_pk_fma_f32 v[122:123], v[148:149], v[14:15], v[122:123] op_sel:[1,0,0] op_sel_hi:[1,1,1]
	v_pk_fma_f32 v[124:125], v[148:149], v[16:17], v[124:125] op_sel:[1,0,0] op_sel_hi:[1,1,1]
	v_pk_fma_f32 v[126:127], v[154:155], v[14:15], v[126:127] op_sel:[0,0,0] op_sel_hi:[0,1,1]
	v_pk_fma_f32 v[128:129], v[154:155], v[16:17], v[128:129] op_sel:[0,0,0] op_sel_hi:[0,1,1]
	v_pk_fma_f32 v[130:131], v[0:1], v[14:15], v[130:131] op_sel:[0,0,0] op_sel_hi:[0,1,1]
	v_pk_fma_f32 v[132:133], v[0:1], v[16:17], v[132:133] op_sel:[0,0,0] op_sel_hi:[0,1,1]
	s_waitcnt vmcnt(0)
	s_load_dwordx2 s[0:1], s[42:43], 0x100
	v_lshl_add_u32 v155, s40, 2, v160
	v_lshlrev_b32_e32 v156, 10, v155
	v_lshl_add_u32 v156, v159, 4, v156
	v_lshlrev_b32_e32 v157, 5, v155
	v_lshrrev_b32_e32 v173, 2, v159
	v_lshl_add_u32 v157, v173, 3, v157
	v_and_b32_e32 v173, 3, v159
	v_cmp_eq_u32_e32 vcc, 0, v173
	s_waitcnt lgkmcnt(0)
	s_add_u32 s4, s0, 0x4780000
	s_addc_u32 s5, s1, 0
	s_add_u32 s6, s0, 0x4f80000
	s_addc_u32 s7, s1, 0
	global_store_dwordx4 v156, v[118:121], s[4:5]
	global_store_dwordx4 v156, v[122:125], s[4:5] offset:256
	global_store_dwordx4 v156, v[126:129], s[4:5] offset:512
	global_store_dwordx4 v156, v[130:133], s[4:5] offset:768
	s_and_saveexec_b64 s[2:3], vcc
	global_store_dwordx2 v157, v[134:135], s[6:7]
	s_branch .LBB0_321
